# baseline (speedup 1.0000x reference)
; #define PG8_STAGE(bufoff, gbase, voff) do { _Pragma("unroll") for (int _i = 0; _i < 2; ++_i) \
;         __builtin_amdgcn_global_load_lds((const unsigned*)((const char*)(gbase) + (voff)[_i]), (LAS unsigned*)(lds + (bufoff) + ldsw + _i * 8192), 16, 0, 0); } while (0)
; #define PG8_LDA(dst, b, h) do { _Pragma("unroll") for (int m = 0; m < 4; ++m) _Pragma("unroll") for (int k = 0; k < 2; ++k) dst[m][k] = *(const LAS bf16x8*)(lds + PG8_SA(b, h) + aoff + m * 2048 + k * 1024); } while (0)
; #define PG8_LDB(dst, b, h) do { _Pragma("unroll") for (int n = 0; n < 2; ++n) _Pragma("unroll") for (int k = 0; k < 2; ++k) dst[n][k] = *(const LAS bf16x8*)(lds + PG8_SB(b, h) + boff + n * 2048 + k * 1024); } while (0)
; #define PG8_MMA(ai, bj, At, Bt) do { __builtin_amdgcn_s_setprio(1); _Pragma("unroll") for (int m = 0; m < 4; ++m) _Pragma("unroll") for (int n = 0; n < 2; ++n) _Pragma("unroll") for (int k = 0; k < 2; ++k) \
;         acc[ai][bj][m][n] = __builtin_amdgcn_mfma_f32_16x16x32_bf16(Bt[n][k], At[m][k], acc[ai][bj][m][n], 0, 0, 0); __builtin_amdgcn_s_setprio(0); } while (0)
; #define PG8_WAIT_L(n) asm volatile("s_waitcnt lgkmcnt(" #n ")" ::: "memory")
; #define PG8_BAR __builtin_amdgcn_s_barrier()
; #define PG8_SCHED __builtin_amdgcn_sched_barrier(0)
; template <class Epi>
; __device__ __forceinline__ void gemm_phase(const int tid, LAS unsigned char* lds, const Gemm g, const StaticOrder& S, const Epi& E) {
;     ...
;             PG8_LDB(B0, 0, 0); PG8_SCHED; PG8_LDA(At, 0, 0);
;             PG8_WAIT_L(8); PG8_BAR; PG8_WAIT_L(0); PG8_MMA(0, 0, At, B0); PG8_BAR; PG8_SCHED;
;             PG8_LDB(B1, 0, 1); PG8_STAGE(PG8_SB(0, 0), b2, voffB);
;             PG8_BAR; PG8_WAIT_L(0); PG8_MMA(0, 1, At, B1); PG8_BAR;
;             PG8_LDA(At, 0, 1); PG8_STAGE(PG8_SA(0, 0), a2, voffA);
;             PG8_BAR; PG8_WAIT_L(0); PG8_MMA(1, 0, At, B0); PG8_BAR; PG8_SCHED;
;     ...
;         for (int a = 0; a < 2; ++a)
; #pragma unroll
;             for (int b = 0; b < 2; ++b)
; #pragma unroll
;                 for (int m = 0; m < 4; ++m)
; #pragma unroll
;                     for (int n = 0; n < 2; ++n) acc[a][b][m][n] = (f32x4){0.f, 0.f, 0.f, 0.f};
.LBB0_335:
	v_mov_b64_e32 v[2:3], 0xae0
	s_ashr_i32 s65, s64, 31
	v_cmp_lt_i64_e32 vcc, s[24:25], v[2:3]
	s_lshl_b64 s[24:25], s[64:65], 20
	s_add_u32 s60, s62, s24
	s_addc_u32 s61, s63, s25
	s_and_b64 s[24:25], vcc, exec
	s_cselect_b32 s24, s61, s11
	s_cselect_b32 s25, s60, s10
	s_ashr_i32 s23, s22, 31
	s_lshl_b64 s[48:49], s[22:23], 20
	s_add_u32 s56, s30, s48
	s_addc_u32 s57, s36, s49
	s_and_b64 s[48:49], vcc, exec
	s_cselect_b32 s23, s57, s1
	s_cselect_b32 s27, s56, s0
	s_add_u32 s28, s10, 0x100
	s_addc_u32 s39, s11, 0
	s_add_u32 s48, s0, 0x100
	v_mov_b32_e32 v2, 0
	s_addc_u32 s49, s1, 0
	s_mov_b32 s50, -2
	v_mov_b32_e32 v3, v2
	v_mov_b64_e32 v[4:5], 0
	v_mov_b64_e32 v[6:7], 0
	v_mov_b64_e32 v[8:9], 0
	v_mov_b64_e32 v[10:11], 0
	v_mov_b64_e32 v[12:13], 0
	v_mov_b64_e32 v[14:15], 0
	v_mov_b64_e32 v[16:17], 0
	v_mov_b64_e32 v[18:19], 0
	v_mov_b64_e32 v[20:21], 0
	v_mov_b64_e32 v[22:23], 0
	v_mov_b64_e32 v[24:25], 0
	v_mov_b64_e32 v[26:27], 0
	v_mov_b64_e32 v[28:29], 0
	v_mov_b64_e32 v[30:31], 0
	v_mov_b64_e32 v[32:33], 0
	v_mov_b64_e32 v[34:35], 0
	v_mov_b64_e32 v[36:37], 0
	v_mov_b64_e32 v[38:39], 0
	v_mov_b64_e32 v[40:41], 0
	v_mov_b64_e32 v[42:43], 0
	v_mov_b64_e32 v[44:45], 0
	v_mov_b64_e32 v[46:47], 0
	v_mov_b64_e32 v[48:49], 0
	v_mov_b64_e32 v[50:51], 0
	v_mov_b64_e32 v[52:53], 0
	v_mov_b64_e32 v[54:55], 0
	v_mov_b64_e32 v[56:57], 0
	v_mov_b64_e32 v[58:59], 0
	v_mov_b64_e32 v[60:61], 0
	v_mov_b64_e32 v[62:63], 0
	v_mov_b64_e32 v[64:65], 0
	v_mov_b64_e32 v[66:67], 0
	v_mov_b64_e32 v[68:69], 0
	v_mov_b64_e32 v[70:71], 0
	v_mov_b64_e32 v[72:73], 0
	v_mov_b64_e32 v[74:75], 0
	v_mov_b64_e32 v[76:77], 0
	v_mov_b64_e32 v[78:79], 0
	v_mov_b64_e32 v[80:81], 0
	v_mov_b64_e32 v[82:83], 0
	v_mov_b64_e32 v[84:85], 0
	v_mov_b64_e32 v[86:87], 0
	v_mov_b64_e32 v[88:89], 0
	v_mov_b64_e32 v[90:91], 0
	v_mov_b64_e32 v[92:93], 0
	v_mov_b64_e32 v[94:95], 0
	v_mov_b64_e32 v[96:97], 0
	v_mov_b64_e32 v[98:99], 0
	v_mov_b64_e32 v[100:101], 0
	v_mov_b64_e32 v[102:103], 0
	v_mov_b64_e32 v[104:105], 0
	v_mov_b64_e32 v[106:107], 0
	v_mov_b64_e32 v[108:109], 0
	v_mov_b64_e32 v[110:111], 0
	v_mov_b64_e32 v[112:113], 0
	v_mov_b64_e32 v[114:115], 0
	v_mov_b64_e32 v[116:117], 0
	v_mov_b64_e32 v[118:119], 0
	v_mov_b64_e32 v[120:121], 0
	v_mov_b64_e32 v[122:123], 0
	v_mov_b64_e32 v[124:125], 0
	v_mov_b64_e32 v[126:127], 0
	v_mov_b64_e32 v[128:129], 0
	v_add_u32_e32 v243, 0x10000, v221
	v_add_u32_e32 v244, 0x14000, v221
	v_add_u32_e32 v245, 0x18000, v221
	v_add_u32_e32 v252, 0x1c000, v221
.LBB0_336:
	s_add_i32 s51, 0, 0x10000
	ds_read_b128 v[130:133], v243
	ds_read_b128 v[134:137], v243 offset:1024
	ds_read_b128 v[138:141], v243 offset:2048
	ds_read_b128 v[142:145], v243 offset:3072
	s_cmp_eq_u32 s50, 28
	s_cselect_b32 s1, s24, s39
	s_cselect_b32 s0, s25, s28
	s_cselect_b32 s11, s23, s49
	s_cselect_b32 s10, s27, s48
	ds_read_b128 v[146:149], v225
	ds_read_b128 v[150:153], v225 offset:1024
	ds_read_b128 v[154:157], v225 offset:2048
	ds_read_b128 v[158:161], v225 offset:3072
	ds_read_b128 v[162:165], v225 offset:4096
	ds_read_b128 v[166:169], v225 offset:5120
	ds_read_b128 v[170:173], v225 offset:6144
	ds_read_b128 v[174:177], v225 offset:7168
	s_waitcnt lgkmcnt(8)
	s_barrier
	s_setprio 1
	s_waitcnt lgkmcnt(7)
	v_mfma_f32_16x16x32_bf16 v[126:129], v[130:133], v[146:149], v[126:129]
	v_mfma_f32_16x16x32_bf16 v[122:125], v[138:141], v[146:149], v[122:125]
	s_waitcnt lgkmcnt(5)
	v_mfma_f32_16x16x32_bf16 v[110:113], v[130:133], v[154:157], v[110:113]
	v_mfma_f32_16x16x32_bf16 v[106:109], v[138:141], v[154:157], v[106:109]
	s_waitcnt lgkmcnt(3)
	v_mfma_f32_16x16x32_bf16 v[94:97], v[130:133], v[162:165], v[94:97]
	v_mfma_f32_16x16x32_bf16 v[90:93], v[138:141], v[162:165], v[90:93]
	s_waitcnt lgkmcnt(1)
	v_mfma_f32_16x16x32_bf16 v[78:81], v[130:133], v[170:173], v[78:81]
	v_mfma_f32_16x16x32_bf16 v[74:77], v[138:141], v[170:173], v[74:77]
	v_mfma_f32_16x16x32_bf16 v[126:129], v[134:137], v[150:153], v[126:129]
	v_mfma_f32_16x16x32_bf16 v[122:125], v[142:145], v[150:153], v[122:125]
	v_mfma_f32_16x16x32_bf16 v[110:113], v[134:137], v[158:161], v[110:113]
	v_mfma_f32_16x16x32_bf16 v[106:109], v[142:145], v[158:161], v[106:109]
	v_mfma_f32_16x16x32_bf16 v[94:97], v[134:137], v[166:169], v[94:97]
	v_mfma_f32_16x16x32_bf16 v[90:93], v[142:145], v[166:169], v[90:93]
	s_waitcnt lgkmcnt(0)
	v_mfma_f32_16x16x32_bf16 v[78:81], v[134:137], v[174:177], v[78:81]
	v_mfma_f32_16x16x32_bf16 v[74:77], v[142:145], v[174:177], v[74:77]
	s_setprio 0
	s_barrier
	s_add_i32 s54, 0, 0x14000
	s_add_i32 s51, s51, s37
	s_mov_b32 m0, s51
	ds_read_b128 v[178:181], v244
	ds_read_b128 v[182:185], v244 offset:1024
	ds_read_b128 v[186:189], v244 offset:2048
	ds_read_b128 v[190:193], v244 offset:3072
	global_load_lds_dwordx4 v198, s[10:11]
	s_add_i32 m0, s51, 0x2000
	s_nop 0
	global_load_lds_dwordx4 v194, s[10:11]
	s_barrier
	s_setprio 1
	s_waitcnt lgkmcnt(3)
	v_mfma_f32_16x16x32_bf16 v[118:121], v[178:181], v[146:149], v[118:121]
	s_waitcnt lgkmcnt(1)
	v_mfma_f32_16x16x32_bf16 v[114:117], v[186:189], v[146:149], v[114:117]
	v_mfma_f32_16x16x32_bf16 v[102:105], v[178:181], v[154:157], v[102:105]
	v_mfma_f32_16x16x32_bf16 v[98:101], v[186:189], v[154:157], v[98:101]
	v_mfma_f32_16x16x32_bf16 v[86:89], v[178:181], v[162:165], v[86:89]
	v_mfma_f32_16x16x32_bf16 v[82:85], v[186:189], v[162:165], v[82:85]
	v_mfma_f32_16x16x32_bf16 v[70:73], v[178:181], v[170:173], v[70:73]
	v_mfma_f32_16x16x32_bf16 v[66:69], v[186:189], v[170:173], v[66:69]
	v_mfma_f32_16x16x32_bf16 v[118:121], v[182:185], v[150:153], v[118:121]
	s_waitcnt lgkmcnt(0)
	v_mfma_f32_16x16x32_bf16 v[114:117], v[190:193], v[150:153], v[114:117]
	v_mfma_f32_16x16x32_bf16 v[102:105], v[182:185], v[158:161], v[102:105]
	v_mfma_f32_16x16x32_bf16 v[98:101], v[190:193], v[158:161], v[98:101]
	v_mfma_f32_16x16x32_bf16 v[86:89], v[182:185], v[166:169], v[86:89]
	v_mfma_f32_16x16x32_bf16 v[82:85], v[190:193], v[166:169], v[82:85]
	v_mfma_f32_16x16x32_bf16 v[70:73], v[182:185], v[174:177], v[70:73]
	v_mfma_f32_16x16x32_bf16 v[66:69], v[190:193], v[174:177], v[66:69]
	s_setprio 0
	s_mov_b32 m0, s46
	s_barrier
; #define PG8_STAGE(bufoff, gbase, voff) do { _Pragma("unroll") for (int _i = 0; _i < 2; ++_i) \
;         __builtin_amdgcn_global_load_lds((const unsigned*)((const char*)(gbase) + (voff)[_i]), (LAS unsigned*)(lds + (bufoff) + ldsw + _i * 8192), 16, 0, 0); } while (0)
; #define PG8_WAIT_V(n) asm volatile("s_waitcnt vmcnt(" #n ")" ::: "memory")
; #define PG8_BAR __builtin_amdgcn_s_barrier()
; template <class Epi>
; __device__ __forceinline__ void gemm_phase(const int tid, LAS unsigned char* lds, const Gemm g, const StaticOrder& S, const Epi& E) {
;     ...
;             PG8_LDB(B0, 0, 0); PG8_SCHED; PG8_LDA(At, 0, 0);
;             PG8_WAIT_L(8); PG8_BAR; PG8_WAIT_L(0); PG8_MMA(0, 0, At, B0); PG8_BAR; PG8_SCHED;
;             PG8_LDB(B1, 0, 1); PG8_STAGE(PG8_SB(0, 0), b2, voffB);
;             PG8_BAR; PG8_WAIT_L(0); PG8_MMA(0, 1, At, B1); PG8_BAR;
;             PG8_LDA(At, 0, 1); PG8_STAGE(PG8_SA(0, 0), a2, voffA);
;             PG8_BAR; PG8_WAIT_L(0); PG8_MMA(1, 0, At, B0); PG8_BAR; PG8_SCHED;
;             PG8_STAGE(PG8_SB(0, 1), b2 + hstep, voffB);
;             { const int first_ = __builtin_amdgcn_readfirstlane((ui > 0 && t == 0) ? 1 : 0);
;               if constexpr (Epi::SMIN == 8) asm volatile("s_cmp_eq_u32 %0, 0\n\ts_cbranch_scc1 .Lws_a%=\n\ts_waitcnt vmcnt(14)\n\ts_branch .Lws_b%=\n.Lws_a%=:\n\ts_waitcnt vmcnt(6)\n.Lws_b%=:" :: "s"(first_) : "memory", "scc");
;               else if constexpr (Epi::SMIN == 24) asm volatile("s_cmp_eq_u32 %0, 0\n\ts_cbranch_scc1 .Lws_a%=\n\ts_waitcnt vmcnt(30)\n\ts_branch .Lws_b%=\n.Lws_a%=:\n\ts_waitcnt vmcnt(6)\n.Lws_b%=:" :: "s"(first_) : "memory", "scc");
;               else PG8_WAIT_V(6); }
;             PG8_BAR; PG8_MMA(1, 1, At, B1); PG8_BAR;
;             PG8_LDB(B0, 1, 0); PG8_SCHED; PG8_LDA(At, 1, 0); PG8_STAGE(PG8_SA(0, 1), a2 + hstep, voffA);
;             PG8_WAIT_L(8); PG8_BAR; PG8_WAIT_L(0); PG8_MMA(0, 0, At, B0); PG8_BAR; PG8_SCHED;
;             PG8_LDB(B1, 1, 1); PG8_STAGE(PG8_SB(1, 0), b3, voffB);
;             PG8_BAR; PG8_WAIT_L(0); PG8_MMA(0, 1, At, B1); PG8_BAR;
;             PG8_LDA(At, 1, 1); PG8_STAGE(PG8_SA(1, 0), a3, voffA);
;             PG8_BAR; PG8_WAIT_L(0); PG8_MMA(1, 0, At, B0); PG8_BAR; PG8_SCHED;
;             PG8_STAGE(PG8_SB(1, 1), b3 + hstep, voffB);
;             PG8_WAIT_V(6); PG8_BAR; PG8_STAGE(PG8_SA(1, 1), a3 + hstep, voffA);
;             PG8_MMA(1, 1, At, B1); PG8_BAR;
	ds_read_b128 v[146:149], v225 offset:16384
	ds_read_b128 v[150:153], v225 offset:17408
	ds_read_b128 v[154:157], v225 offset:18432
	ds_read_b128 v[158:161], v225 offset:19456
	ds_read_b128 v[162:165], v225 offset:20480
	ds_read_b128 v[166:169], v225 offset:21504
	ds_read_b128 v[170:173], v225 offset:22528
	ds_read_b128 v[174:177], v225 offset:23552
	global_load_lds_dwordx4 v200, s[0:1]
	s_mov_b32 m0, s47
	s_nop 0
	global_load_lds_dwordx4 v196, s[0:1]
	s_barrier
	s_setprio 1
	s_waitcnt lgkmcnt(7)
	v_mfma_f32_16x16x32_bf16 v[62:65], v[130:133], v[146:149], v[62:65]
	v_mfma_f32_16x16x32_bf16 v[58:61], v[138:141], v[146:149], v[58:61]
	s_waitcnt lgkmcnt(5)
	v_mfma_f32_16x16x32_bf16 v[46:49], v[130:133], v[154:157], v[46:49]
	v_mfma_f32_16x16x32_bf16 v[42:45], v[138:141], v[154:157], v[42:45]
	s_waitcnt lgkmcnt(3)
	v_mfma_f32_16x16x32_bf16 v[30:33], v[130:133], v[162:165], v[30:33]
	v_mfma_f32_16x16x32_bf16 v[26:29], v[138:141], v[162:165], v[26:29]
	s_waitcnt lgkmcnt(1)
	v_mfma_f32_16x16x32_bf16 v[14:17], v[130:133], v[170:173], v[14:17]
	v_mfma_f32_16x16x32_bf16 v[10:13], v[138:141], v[170:173], v[10:13]
	v_mfma_f32_16x16x32_bf16 v[62:65], v[134:137], v[150:153], v[62:65]
	v_mfma_f32_16x16x32_bf16 v[58:61], v[142:145], v[150:153], v[58:61]
	v_mfma_f32_16x16x32_bf16 v[46:49], v[134:137], v[158:161], v[46:49]
	v_mfma_f32_16x16x32_bf16 v[42:45], v[142:145], v[158:161], v[42:45]
	v_mfma_f32_16x16x32_bf16 v[30:33], v[134:137], v[166:169], v[30:33]
	v_mfma_f32_16x16x32_bf16 v[26:29], v[142:145], v[166:169], v[26:29]
	s_waitcnt lgkmcnt(0)
	v_mfma_f32_16x16x32_bf16 v[14:17], v[134:137], v[174:177], v[14:17]
	v_mfma_f32_16x16x32_bf16 v[10:13], v[142:145], v[174:177], v[10:13]
	s_setprio 0
	s_barrier
	s_add_u32 s66, s10, 0x80000
	s_addc_u32 s67, s11, 0
	s_add_i32 s51, s54, s37
	s_mov_b32 m0, s51
	s_nop 0
	global_load_lds_dwordx4 v198, s[66:67]
	s_add_i32 m0, s51, 0x2000
	s_nop 0
	global_load_lds_dwordx4 v194, s[66:67]
	s_waitcnt vmcnt(6)
	s_barrier
	s_setprio 1
	v_mfma_f32_16x16x32_bf16 v[54:57], v[178:181], v[146:149], v[54:57]
	v_mfma_f32_16x16x32_bf16 v[50:53], v[186:189], v[146:149], v[50:53]
	v_mfma_f32_16x16x32_bf16 v[38:41], v[178:181], v[154:157], v[38:41]
	v_mfma_f32_16x16x32_bf16 v[34:37], v[186:189], v[154:157], v[34:37]
	v_mfma_f32_16x16x32_bf16 v[22:25], v[178:181], v[162:165], v[22:25]
	v_mfma_f32_16x16x32_bf16 v[18:21], v[186:189], v[162:165], v[18:21]
	v_mfma_f32_16x16x32_bf16 v[6:9], v[178:181], v[170:173], v[6:9]
	v_mfma_f32_16x16x32_bf16 v[2:5], v[186:189], v[170:173], v[2:5]
	v_mfma_f32_16x16x32_bf16 v[54:57], v[182:185], v[150:153], v[54:57]
	v_mfma_f32_16x16x32_bf16 v[50:53], v[190:193], v[150:153], v[50:53]
	v_mfma_f32_16x16x32_bf16 v[38:41], v[182:185], v[158:161], v[38:41]
	v_mfma_f32_16x16x32_bf16 v[34:37], v[190:193], v[158:161], v[34:37]
	v_mfma_f32_16x16x32_bf16 v[22:25], v[182:185], v[166:169], v[22:25]
	v_mfma_f32_16x16x32_bf16 v[18:21], v[190:193], v[166:169], v[18:21]
	v_mfma_f32_16x16x32_bf16 v[6:9], v[182:185], v[174:177], v[6:9]
	v_mfma_f32_16x16x32_bf16 v[2:5], v[190:193], v[174:177], v[2:5]
	s_setprio 0
	s_add_i32 s51, 0, 0x18000
	s_barrier
	ds_read_b128 v[130:133], v245
	ds_read_b128 v[134:137], v245 offset:1024
	ds_read_b128 v[138:141], v245 offset:2048
	ds_read_b128 v[142:145], v245 offset:3072
	s_add_u32 s66, s0, 0x80000
	s_addc_u32 s67, s1, 0
	s_mov_b32 m0, s58
	ds_read_b128 v[146:149], v225 offset:32768
	ds_read_b128 v[150:153], v225 offset:33792
	ds_read_b128 v[154:157], v225 offset:34816
	ds_read_b128 v[158:161], v225 offset:35840
	ds_read_b128 v[162:165], v225 offset:36864
	ds_read_b128 v[166:169], v225 offset:37888
	ds_read_b128 v[170:173], v225 offset:38912
	ds_read_b128 v[174:177], v225 offset:39936
	global_load_lds_dwordx4 v200, s[66:67]
	s_mov_b32 m0, s59
	s_nop 0
	global_load_lds_dwordx4 v196, s[66:67]
	s_waitcnt lgkmcnt(8)
	s_barrier
	s_setprio 1
	s_waitcnt lgkmcnt(7)
	v_mfma_f32_16x16x32_bf16 v[126:129], v[130:133], v[146:149], v[126:129]
	v_mfma_f32_16x16x32_bf16 v[122:125], v[138:141], v[146:149], v[122:125]
	s_waitcnt lgkmcnt(5)
	v_mfma_f32_16x16x32_bf16 v[110:113], v[130:133], v[154:157], v[110:113]
	v_mfma_f32_16x16x32_bf16 v[106:109], v[138:141], v[154:157], v[106:109]
	s_waitcnt lgkmcnt(3)
	v_mfma_f32_16x16x32_bf16 v[94:97], v[130:133], v[162:165], v[94:97]
	v_mfma_f32_16x16x32_bf16 v[90:93], v[138:141], v[162:165], v[90:93]
	s_waitcnt lgkmcnt(1)
	v_mfma_f32_16x16x32_bf16 v[78:81], v[130:133], v[170:173], v[78:81]
	v_mfma_f32_16x16x32_bf16 v[74:77], v[138:141], v[170:173], v[74:77]
	v_mfma_f32_16x16x32_bf16 v[126:129], v[134:137], v[150:153], v[126:129]
	v_mfma_f32_16x16x32_bf16 v[122:125], v[142:145], v[150:153], v[122:125]
	v_mfma_f32_16x16x32_bf16 v[110:113], v[134:137], v[158:161], v[110:113]
	v_mfma_f32_16x16x32_bf16 v[106:109], v[142:145], v[158:161], v[106:109]
	v_mfma_f32_16x16x32_bf16 v[94:97], v[134:137], v[166:169], v[94:97]
	v_mfma_f32_16x16x32_bf16 v[90:93], v[142:145], v[166:169], v[90:93]
	s_waitcnt lgkmcnt(0)
	v_mfma_f32_16x16x32_bf16 v[78:81], v[134:137], v[174:177], v[78:81]
	v_mfma_f32_16x16x32_bf16 v[74:77], v[142:145], v[174:177], v[74:77]
	s_setprio 0
	s_barrier
	s_add_i32 s54, 0, 0x1c000
	s_add_i32 s51, s51, s37
	s_add_i32 m0, s51, 0xffffff80
	ds_read_b128 v[178:181], v252
	ds_read_b128 v[182:185], v252 offset:1024
	ds_read_b128 v[186:189], v252 offset:2048
	ds_read_b128 v[190:193], v252 offset:3072
	global_load_lds_dwordx4 v198, s[10:11] offset:128
	s_add_i32 m0, s51, 0x1f80
	s_nop 0
	global_load_lds_dwordx4 v194, s[10:11] offset:128
	s_barrier
; #define PG8_STAGE(bufoff, gbase, voff) do { _Pragma("unroll") for (int _i = 0; _i < 2; ++_i) \
;         __builtin_amdgcn_global_load_lds((const unsigned*)((const char*)(gbase) + (voff)[_i]), (LAS unsigned*)(lds + (bufoff) + ldsw + _i * 8192), 16, 0, 0); } while (0)
; #define PG8_LDA(dst, b, h) do { _Pragma("unroll") for (int m = 0; m < 4; ++m) _Pragma("unroll") for (int k = 0; k < 2; ++k) dst[m][k] = *(const LAS bf16x8*)(lds + PG8_SA(b, h) + aoff + m * 2048 + k * 1024); } while (0)
; #define PG8_LDB(dst, b, h) do { _Pragma("unroll") for (int n = 0; n < 2; ++n) _Pragma("unroll") for (int k = 0; k < 2; ++k) dst[n][k] = *(const LAS bf16x8*)(lds + PG8_SB(b, h) + boff + n * 2048 + k * 1024); } while (0)
; #define PG8_MMA(ai, bj, At, Bt) do { __builtin_amdgcn_s_setprio(1); _Pragma("unroll") for (int m = 0; m < 4; ++m) _Pragma("unroll") for (int n = 0; n < 2; ++n) _Pragma("unroll") for (int k = 0; k < 2; ++k) \
;         acc[ai][bj][m][n] = __builtin_amdgcn_mfma_f32_16x16x32_bf16(Bt[n][k], At[m][k], acc[ai][bj][m][n], 0, 0, 0); __builtin_amdgcn_s_setprio(0); } while (0)
; #define PG8_WAIT_V(n) asm volatile("s_waitcnt vmcnt(" #n ")" ::: "memory")
; #define PG8_WAIT_L(n) asm volatile("s_waitcnt lgkmcnt(" #n ")" ::: "memory")
; #define PG8_BAR __builtin_amdgcn_s_barrier()
; template <class Epi>
; __device__ __forceinline__ void gemm_phase(const int tid, LAS unsigned char* lds, const Gemm g, const StaticOrder& S, const Epi& E) {
;     ...
;             PG8_LDB(B0, 1, 0); PG8_SCHED; PG8_LDA(At, 1, 0); PG8_STAGE(PG8_SA(0, 1), a2 + hstep, voffA);
;             PG8_WAIT_L(8); PG8_BAR; PG8_WAIT_L(0); PG8_MMA(0, 0, At, B0); PG8_BAR; PG8_SCHED;
;             PG8_LDB(B1, 1, 1); PG8_STAGE(PG8_SB(1, 0), b3, voffB);
;             PG8_BAR; PG8_WAIT_L(0); PG8_MMA(0, 1, At, B1); PG8_BAR;
;             PG8_LDA(At, 1, 1); PG8_STAGE(PG8_SA(1, 0), a3, voffA);
;             PG8_BAR; PG8_WAIT_L(0); PG8_MMA(1, 0, At, B0); PG8_BAR; PG8_SCHED;
;             PG8_STAGE(PG8_SB(1, 1), b3 + hstep, voffB);
;             PG8_WAIT_V(6); PG8_BAR; PG8_STAGE(PG8_SA(1, 1), a3 + hstep, voffA);
;             PG8_MMA(1, 1, At, B1); PG8_BAR;
;     __device__ __forceinline__ void operator()(const AccT& acc, const pg8::Unit& u, int wr, int wc, int fr, int fq, pg8::RsCache& rsc) const {
;         const int row0 = u.pm * 256 + wr * 64 + fr;
;         if (rsc.pm != u.pm) {
	s_setprio 1
	s_waitcnt lgkmcnt(3)
	v_mfma_f32_16x16x32_bf16 v[118:121], v[178:181], v[146:149], v[118:121]
	s_waitcnt lgkmcnt(1)
	v_mfma_f32_16x16x32_bf16 v[114:117], v[186:189], v[146:149], v[114:117]
	v_mfma_f32_16x16x32_bf16 v[102:105], v[178:181], v[154:157], v[102:105]
	v_mfma_f32_16x16x32_bf16 v[98:101], v[186:189], v[154:157], v[98:101]
	v_mfma_f32_16x16x32_bf16 v[86:89], v[178:181], v[162:165], v[86:89]
	v_mfma_f32_16x16x32_bf16 v[82:85], v[186:189], v[162:165], v[82:85]
	v_mfma_f32_16x16x32_bf16 v[70:73], v[178:181], v[170:173], v[70:73]
	v_mfma_f32_16x16x32_bf16 v[66:69], v[186:189], v[170:173], v[66:69]
	v_mfma_f32_16x16x32_bf16 v[118:121], v[182:185], v[150:153], v[118:121]
	s_waitcnt lgkmcnt(0)
	v_mfma_f32_16x16x32_bf16 v[114:117], v[190:193], v[150:153], v[114:117]
	v_mfma_f32_16x16x32_bf16 v[102:105], v[182:185], v[158:161], v[102:105]
	v_mfma_f32_16x16x32_bf16 v[98:101], v[190:193], v[158:161], v[98:101]
	v_mfma_f32_16x16x32_bf16 v[86:89], v[182:185], v[166:169], v[86:89]
	v_mfma_f32_16x16x32_bf16 v[82:85], v[190:193], v[166:169], v[82:85]
	v_mfma_f32_16x16x32_bf16 v[70:73], v[182:185], v[174:177], v[70:73]
	v_mfma_f32_16x16x32_bf16 v[66:69], v[190:193], v[174:177], v[66:69]
	s_setprio 0
	s_add_i32 m0, s68, 0xffffff80
	s_barrier
	ds_read_b128 v[146:149], v225 offset:49152
	ds_read_b128 v[150:153], v225 offset:50176
	ds_read_b128 v[154:157], v225 offset:51200
	ds_read_b128 v[158:161], v225 offset:52224
	ds_read_b128 v[162:165], v225 offset:53248
	ds_read_b128 v[166:169], v225 offset:54272
	ds_read_b128 v[170:173], v225 offset:55296
	ds_read_b128 v[174:177], v225 offset:56320
	global_load_lds_dwordx4 v200, s[0:1] offset:128
	s_add_i32 m0, s69, 0xffffff80
	s_nop 0
	global_load_lds_dwordx4 v196, s[0:1] offset:128
	s_barrier
	s_setprio 1
	s_waitcnt lgkmcnt(7)
	v_mfma_f32_16x16x32_bf16 v[62:65], v[130:133], v[146:149], v[62:65]
	v_mfma_f32_16x16x32_bf16 v[58:61], v[138:141], v[146:149], v[58:61]
	s_waitcnt lgkmcnt(5)
	v_mfma_f32_16x16x32_bf16 v[46:49], v[130:133], v[154:157], v[46:49]
	v_mfma_f32_16x16x32_bf16 v[42:45], v[138:141], v[154:157], v[42:45]
	s_waitcnt lgkmcnt(3)
	v_mfma_f32_16x16x32_bf16 v[30:33], v[130:133], v[162:165], v[30:33]
	v_mfma_f32_16x16x32_bf16 v[26:29], v[138:141], v[162:165], v[26:29]
	s_waitcnt lgkmcnt(1)
	v_mfma_f32_16x16x32_bf16 v[14:17], v[130:133], v[170:173], v[14:17]
	v_mfma_f32_16x16x32_bf16 v[10:13], v[138:141], v[170:173], v[10:13]
	v_mfma_f32_16x16x32_bf16 v[62:65], v[134:137], v[150:153], v[62:65]
	v_mfma_f32_16x16x32_bf16 v[58:61], v[142:145], v[150:153], v[58:61]
	v_mfma_f32_16x16x32_bf16 v[46:49], v[134:137], v[158:161], v[46:49]
	v_mfma_f32_16x16x32_bf16 v[42:45], v[142:145], v[158:161], v[42:45]
	v_mfma_f32_16x16x32_bf16 v[30:33], v[134:137], v[166:169], v[30:33]
	v_mfma_f32_16x16x32_bf16 v[26:29], v[142:145], v[166:169], v[26:29]
	s_waitcnt lgkmcnt(0)
	v_mfma_f32_16x16x32_bf16 v[14:17], v[134:137], v[174:177], v[14:17]
	v_mfma_f32_16x16x32_bf16 v[10:13], v[142:145], v[174:177], v[10:13]
	s_setprio 0
	s_barrier
	s_add_u32 s10, s10, 0x80080
	s_addc_u32 s11, s11, 0
	s_add_i32 s51, s54, s37
	s_mov_b32 m0, s51
	s_nop 0
	global_load_lds_dwordx4 v198, s[10:11]
	s_add_i32 m0, s51, 0x2000
	s_add_u32 s0, s0, 0x80080
	s_addc_u32 s1, s1, 0
	global_load_lds_dwordx4 v194, s[10:11]
	s_mov_b32 m0, s84
	s_waitcnt vmcnt(6)
	s_barrier
	global_load_lds_dwordx4 v200, s[0:1]
	s_mov_b32 m0, s85
	s_nop 0
	global_load_lds_dwordx4 v196, s[0:1]
	s_setprio 1
	v_mfma_f32_16x16x32_bf16 v[54:57], v[178:181], v[146:149], v[54:57]
	v_mfma_f32_16x16x32_bf16 v[50:53], v[186:189], v[146:149], v[50:53]
	v_mfma_f32_16x16x32_bf16 v[38:41], v[178:181], v[154:157], v[38:41]
	v_mfma_f32_16x16x32_bf16 v[34:37], v[186:189], v[154:157], v[34:37]
	v_mfma_f32_16x16x32_bf16 v[22:25], v[178:181], v[162:165], v[22:25]
	v_mfma_f32_16x16x32_bf16 v[18:21], v[186:189], v[162:165], v[18:21]
	v_mfma_f32_16x16x32_bf16 v[6:9], v[178:181], v[170:173], v[6:9]
	v_mfma_f32_16x16x32_bf16 v[2:5], v[186:189], v[170:173], v[2:5]
	v_mfma_f32_16x16x32_bf16 v[54:57], v[182:185], v[150:153], v[54:57]
	v_mfma_f32_16x16x32_bf16 v[50:53], v[190:193], v[150:153], v[50:53]
	v_mfma_f32_16x16x32_bf16 v[38:41], v[182:185], v[158:161], v[38:41]
	v_mfma_f32_16x16x32_bf16 v[34:37], v[190:193], v[158:161], v[34:37]
	v_mfma_f32_16x16x32_bf16 v[22:25], v[182:185], v[166:169], v[22:25]
	v_mfma_f32_16x16x32_bf16 v[18:21], v[190:193], v[166:169], v[18:21]
	v_mfma_f32_16x16x32_bf16 v[6:9], v[182:185], v[174:177], v[6:9]
	v_mfma_f32_16x16x32_bf16 v[2:5], v[190:193], v[174:177], v[2:5]
	s_setprio 0
	s_add_i32 s50, s50, 2
	s_add_u32 s28, s28, 0x100
	s_addc_u32 s39, s39, 0
	s_add_u32 s48, s48, 0x100
	s_addc_u32 s49, s49, 0
	s_cmp_gt_u32 s50, 29
	s_barrier
	s_cbranch_scc0 .LBB0_336
	v_lshl_add_u32 v212, s95, 8, v220
	s_cmp_eq_u32 s26, s95
	v_or_b32_e32 v218, 16, v212
	v_or_b32_e32 v216, 32, v212
	v_or_b32_e32 v214, 48, v212
	s_cbranch_scc1 .LBB0_341
; __device__ __forceinline__ void rows_rstd4(const float* ssqp, int rbase, int fq, float (&rs)[4]) {
;     f32x4 pa_[4], pb_[4];
; #pragma unroll
;     for (int m = 0; m < 4; ++m) { const float* q = ssqp + (size_t)(rbase + m * 16) * 32 + 8 * fq; pa_[m] = *(const f32x4*)q; pb_[m] = *(const f32x4*)(q + 4); }
;     asm volatile("" ::: "memory");
; #pragma unroll
;     for (int m = 0; m < 4; ++m) { const f32x4 a = pa_[m], b = pb_[m];
;         float t = ((a[0] + a[1]) + (a[2] + a[3])) + ((b[0] + b[1]) + (b[2] + b[3]));
;         t = xadd<16>(t); t = xadd<32>(t);
;         rs[m] = __builtin_amdgcn_rsqf(t * (1.0f / DM) + EPS); }
; }
;     __device__ __forceinline__ void operator()(const AccT& acc, const pg8::Unit& u, int wr, int wc, int fr, int fq, pg8::RsCache& rsc) const {
;     ...
;         if (rsc.pm != u.pm) {
;             float r0[4], r1[4]; rows_rstd4(ssq, row0, fq, r0); rows_rstd4(ssq, row0 + 128, fq, r1);
;             if (fq == 0) {
; #pragma unroll
;                 for (int m = 0; m < 4; ++m) { rsc.rl[m * 16 + fr] = r0[m]; rsc.rl[64 + m * 16 + fr] = r1[m]; } }
;             rsc.pm = u.pm; asm volatile("s_waitcnt lgkmcnt(0)" ::: "memory"); }
	v_ashrrev_i32_e32 v213, 31, v212
	v_lshlrev_b64 v[130:131], 7, v[212:213]
	v_lshl_add_u64 v[130:131], v[204:205], 0, v[130:131]
	global_load_dwordx4 v[132:135], v[130:131], off offset:16
	global_load_dwordx4 v[136:139], v[130:131], off
	v_ashrrev_i32_e32 v219, 31, v218
	v_lshlrev_b64 v[140:141], 7, v[218:219]
	v_lshl_add_u64 v[144:145], v[204:205], 0, v[140:141]
	global_load_dwordx4 v[140:143], v[144:145], off offset:16
	s_nop 0
	global_load_dwordx4 v[144:147], v[144:145], off
	v_ashrrev_i32_e32 v217, 31, v216
	v_lshlrev_b64 v[148:149], 7, v[216:217]
	v_lshl_add_u64 v[152:153], v[204:205], 0, v[148:149]
	global_load_dwordx4 v[148:151], v[152:153], off offset:16
	s_nop 0
	global_load_dwordx4 v[152:155], v[152:153], off
	v_ashrrev_i32_e32 v215, 31, v214
	v_lshlrev_b64 v[156:157], 7, v[214:215]
	v_lshl_add_u64 v[160:161], v[204:205], 0, v[156:157]
	global_load_dwordx4 v[156:159], v[160:161], off offset:16
	s_nop 0
	global_load_dwordx4 v[160:163], v[160:161], off
	s_mov_b64 s[0:1], 0x4000
	s_waitcnt vmcnt(0)
	v_add_f32_e32 v132, v132, v133
	v_add_f32_e32 v0, v136, v137
	v_add_f32_e32 v136, v138, v139
	v_add_f32_e32 v133, v134, v135
	v_add_f32_e32 v0, v0, v136
	v_add_f32_e32 v132, v132, v133
	v_add_f32_e32 v0, v0, v132
	ds_swizzle_b32 v132, v0 offset:swizzle(SWAP,16)
	v_add_f32_e32 v133, v146, v147
	v_add_f32_e32 v134, v142, v143
	s_waitcnt lgkmcnt(0)
	v_add_f32_e32 v0, v0, v132
	v_add_f32_e32 v132, v144, v145
	v_add_f32_e32 v132, v132, v133
	v_add_f32_e32 v133, v140, v141
	v_add_f32_e32 v133, v133, v134
	v_add_f32_e32 v132, v132, v133
	ds_swizzle_b32 v133, v132 offset:swizzle(SWAP,16)
	v_add_f32_e32 v134, v150, v151
	v_mov_b32_e32 v138, v0
	s_nop 1
	v_permlane32_swap_b32_e32 v0, v138
	s_waitcnt lgkmcnt(0)
	v_add_f32_e32 v139, v132, v133
	v_add_f32_e32 v132, v152, v153
	v_add_f32_e32 v133, v154, v155
	v_add_f32_e32 v132, v132, v133
	v_add_f32_e32 v133, v148, v149
	v_add_f32_e32 v133, v133, v134
	v_add_f32_e32 v132, v132, v133
	ds_swizzle_b32 v133, v132 offset:swizzle(SWAP,16)
	v_add_f32_e32 v134, v158, v159
	v_mov_b32_e32 v140, v139
	s_nop 1
	v_permlane32_swap_b32_e32 v139, v140
	s_waitcnt lgkmcnt(0)
	v_add_f32_e32 v141, v132, v133
	v_add_f32_e32 v132, v160, v161
	v_add_f32_e32 v133, v162, v163
	v_add_f32_e32 v132, v132, v133
	v_add_f32_e32 v133, v156, v157
	v_add_f32_e32 v133, v133, v134
	v_add_f32_e32 v132, v132, v133
	ds_swizzle_b32 v133, v132 offset:swizzle(SWAP,16)
	v_mov_b32_e32 v142, v141
	s_nop 1
	v_permlane32_swap_b32_e32 v141, v142
	s_waitcnt lgkmcnt(0)
	v_add_f32_e32 v143, v132, v133
	v_lshl_add_u64 v[132:133], v[130:131], 0, s[0:1]
	s_movk_i32 s0, 0x4000
	v_add_co_u32_e32 v134, vcc, s0, v130
	s_movk_i32 s0, 0x5000
	s_nop 0
	v_addc_co_u32_e32 v135, vcc, 0, v131, vcc
	v_add_co_u32_e32 v136, vcc, s0, v130
	s_mov_b64 s[0:1], 0x4800
	s_nop 0
	v_addc_co_u32_e32 v137, vcc, 0, v131, vcc
	global_load_dwordx4 v[146:149], v[136:137], off offset:-4096
	global_load_dwordx4 v[150:153], v[132:133], off offset:16
	v_lshl_add_u64 v[132:133], v[130:131], 0, s[0:1]
	s_mov_b64 s[0:1], 0x5000
	global_load_dwordx4 v[154:157], v[134:135], off offset:2048
	global_load_dwordx4 v[158:161], v[132:133], off offset:16
	v_lshl_add_u64 v[132:133], v[130:131], 0, s[0:1]
	s_mov_b64 s[0:1], 0x5800
	v_lshl_add_u64 v[130:131], v[130:131], 0, s[0:1]
	global_load_dwordx4 v[162:165], v[136:137], off
	global_load_dwordx4 v[166:169], v[132:133], off offset:16
	s_nop 0
	global_load_dwordx4 v[134:137], v[136:137], off offset:2048
	s_nop 0
	global_load_dwordx4 v[130:133], v[130:131], off offset:16
	v_mov_b32_e32 v144, v143
	s_nop 1
	v_permlane32_swap_b32_e32 v143, v144
	s_waitcnt vmcnt(7)
	v_add_f32_e32 v145, v146, v147
	v_add_f32_e32 v146, v148, v149
	v_add_f32_e32 v145, v145, v146
	s_waitcnt vmcnt(6)
	v_add_f32_e32 v146, v150, v151
	v_add_f32_e32 v147, v152, v153
	v_add_f32_e32 v146, v146, v147
	s_waitcnt vmcnt(5)
	v_add_f32_e32 v147, v154, v155
	v_add_f32_e32 v148, v156, v157
	v_add_f32_e32 v147, v147, v148
	s_waitcnt vmcnt(4)
	v_add_f32_e32 v148, v158, v159
	v_add_f32_e32 v149, v160, v161
	v_add_f32_e32 v148, v148, v149
	s_waitcnt vmcnt(3)
	v_add_f32_e32 v149, v162, v163
	v_add_f32_e32 v150, v164, v165
	v_add_f32_e32 v149, v149, v150
	s_waitcnt vmcnt(2)
	v_add_f32_e32 v150, v166, v167
	v_add_f32_e32 v151, v168, v169
	s_waitcnt vmcnt(1)
	v_add_f32_e32 v134, v134, v135
	v_add_f32_e32 v135, v136, v137
	s_waitcnt vmcnt(0)
	v_add_f32_e32 v130, v130, v131
	v_add_f32_e32 v131, v132, v133
	v_add_f32_e32 v150, v150, v151
	v_add_f32_e32 v134, v134, v135
	v_add_f32_e32 v130, v130, v131
	v_add_f32_e32 v145, v145, v146
	v_add_f32_e32 v147, v147, v148
	v_add_f32_e32 v149, v149, v150
	v_add_f32_e32 v130, v134, v130
	ds_swizzle_b32 v146, v145 offset:swizzle(SWAP,16)
	ds_swizzle_b32 v148, v147 offset:swizzle(SWAP,16)
	ds_swizzle_b32 v150, v149 offset:swizzle(SWAP,16)
	ds_swizzle_b32 v131, v130 offset:swizzle(SWAP,16)
	s_waitcnt lgkmcnt(3)
	v_add_f32_e32 v145, v145, v146
	s_waitcnt lgkmcnt(2)
	v_add_f32_e32 v147, v147, v148
	s_waitcnt lgkmcnt(1)
	v_add_f32_e32 v149, v149, v150
	s_waitcnt lgkmcnt(0)
	v_add_f32_e32 v130, v130, v131
	v_mov_b32_e32 v146, v145
	v_mov_b32_e32 v148, v147
	v_mov_b32_e32 v150, v149
	v_mov_b32_e32 v131, v130
	v_permlane32_swap_b32_e32 v145, v146
	v_permlane32_swap_b32_e32 v147, v148
	v_permlane32_swap_b32_e32 v149, v150
	v_permlane32_swap_b32_e32 v130, v131
	s_and_saveexec_b64 s[0:1], s[4:5]
	s_cbranch_execz .LBB0_340
	v_add_f32_e32 v136, v139, v140
	v_add_f32_e32 v0, v0, v138
	v_add_f32_e32 v132, v147, v148
	v_add_f32_e32 v133, v145, v146
	v_fmamk_f32 v136, v136, 0x3a000000, v242
	v_fmamk_f32 v0, v0, 0x3a000000, v242
	v_fmamk_f32 v132, v132, 0x3a000000, v242
	v_fmamk_f32 v133, v133, 0x3a000000, v242
	v_add_f32_e32 v134, v143, v144
	v_add_f32_e32 v135, v141, v142
	v_rsq_f32_e32 v136, v136
	v_rsq_f32_e32 v0, v0
	v_add_f32_e32 v130, v130, v131
	v_add_f32_e32 v131, v149, v150
	v_rsq_f32_e32 v132, v132
	v_rsq_f32_e32 v133, v133
	v_fmamk_f32 v134, v134, 0x3a000000, v242
	v_fmamk_f32 v135, v135, 0x3a000000, v242
	v_fmamk_f32 v130, v130, 0x3a000000, v242
	v_fmamk_f32 v131, v131, 0x3a000000, v242
	v_rsq_f32_e32 v134, v134
	v_rsq_f32_e32 v135, v135
	v_rsq_f32_e32 v130, v130
	v_rsq_f32_e32 v131, v131
	ds_write2_b32 v222, v0, v136 offset1:16
	ds_write2_b32 v222, v133, v132 offset0:64 offset1:80
	ds_write2_b32 v222, v135, v134 offset0:32 offset1:48
	ds_write2_b32 v222, v131, v130 offset0:96 offset1:112

; #define PG8_LDA(dst, b, h) do { _Pragma("unroll") for (int m = 0; m < 4; ++m) _Pragma("unroll") for (int k = 0; k < 2; ++k) dst[m][k] = *(const LAS bf16x8*)(lds + PG8_SA(b, h) + aoff + m * 2048 + k * 1024); } while (0)
; #define PG8_LDB(dst, b, h) do { _Pragma("unroll") for (int n = 0; n < 2; ++n) _Pragma("unroll") for (int k = 0; k < 2; ++k) dst[n][k] = *(const LAS bf16x8*)(lds + PG8_SB(b, h) + boff + n * 2048 + k * 1024); } while (0)
; #define PG8_SCHED __builtin_amdgcn_sched_barrier(0)
; template <class Epi>
; __device__ __forceinline__ void gemm_phase(const int tid, LAS unsigned char* lds, const Gemm g, const StaticOrder& S, const Epi& E) {
;     ...
;         const bool has_next = S.next(ui + 1, nxt);
;         const char* nA = has_next ? (const char*)g.A + (size_t)nxt.pm * tstep : cA; const char* nB = has_next ? (const char*)g.Bt + (size_t)nxt.pn * tstep : cB;
;         for (int t = 0; t < nt; t += 2) {
;             const bool last = (t == nt - 2);
;             const char* a2 = last ? nA : cA + (size_t)(t + 2) * kstep; const char* b2 = last ? nB : cB + (size_t)(t + 2) * kstep;
;             const char* a3 = a2 + kstep; const char* b3 = b2 + kstep;
;             PG8_LDB(B0, 0, 0); PG8_SCHED; PG8_LDA(At, 0, 0);
;     ...
; #pragma unroll
;         for (int a = 0; a < 2; ++a)
; #pragma unroll
;             for (int b = 0; b < 2; ++b)
; #pragma unroll
;                 for (int m = 0; m < 4; ++m)
; #pragma unroll
;                     for (int n = 0; n < 2; ++n) acc[a][b][m][n] = (f32x4){0.f, 0.f, 0.f, 0.f};
.LBB0_418:
	s_cmp_lg_u32 s12, 0
	s_cselect_b64 s[12:13], -1, 0
	s_add_u32 s60, s16, 0x100
	s_addc_u32 s61, s17, 0
	s_add_u32 s64, s14, 0x100
	v_mov_b32_e32 v2, 0
	s_mov_b32 s66, 0
	s_addc_u32 s65, s15, 0
	v_mov_b32_e32 v3, v2
	v_mov_b64_e32 v[4:5], 0
	v_mov_b64_e32 v[6:7], 0
	v_mov_b64_e32 v[8:9], 0
	v_mov_b64_e32 v[10:11], 0
	v_mov_b64_e32 v[12:13], 0
	v_mov_b64_e32 v[14:15], 0
	v_mov_b64_e32 v[16:17], 0
	v_mov_b64_e32 v[18:19], 0
	v_mov_b64_e32 v[20:21], 0
	v_mov_b64_e32 v[22:23], 0
	v_mov_b64_e32 v[24:25], 0
	v_mov_b64_e32 v[26:27], 0
	v_mov_b64_e32 v[28:29], 0
	v_mov_b64_e32 v[30:31], 0
	v_mov_b64_e32 v[32:33], 0
	v_mov_b64_e32 v[34:35], 0
	v_mov_b64_e32 v[36:37], 0
	v_mov_b64_e32 v[38:39], 0
	v_mov_b64_e32 v[40:41], 0
	v_mov_b64_e32 v[42:43], 0
	v_mov_b64_e32 v[44:45], 0
	v_mov_b64_e32 v[46:47], 0
	v_mov_b64_e32 v[48:49], 0
	v_mov_b64_e32 v[50:51], 0
	v_mov_b64_e32 v[52:53], 0
	v_mov_b64_e32 v[54:55], 0
	v_mov_b64_e32 v[56:57], 0
	v_mov_b64_e32 v[58:59], 0
	v_mov_b64_e32 v[60:61], 0
	v_mov_b64_e32 v[62:63], 0
	v_mov_b64_e32 v[64:65], 0
	v_mov_b64_e32 v[66:67], 0
	v_mov_b64_e32 v[68:69], 0
	v_mov_b64_e32 v[70:71], 0
	v_mov_b64_e32 v[72:73], 0
	v_mov_b64_e32 v[74:75], 0
	v_mov_b64_e32 v[76:77], 0
	v_mov_b64_e32 v[78:79], 0
	v_mov_b64_e32 v[80:81], 0
	v_mov_b64_e32 v[82:83], 0
	v_mov_b64_e32 v[84:85], 0
	v_mov_b64_e32 v[86:87], 0
	v_mov_b64_e32 v[88:89], 0
	v_mov_b64_e32 v[90:91], 0
	v_mov_b64_e32 v[92:93], 0
	v_mov_b64_e32 v[94:95], 0
	v_mov_b64_e32 v[96:97], 0
	v_mov_b64_e32 v[98:99], 0
	v_mov_b64_e32 v[100:101], 0
	v_mov_b64_e32 v[102:103], 0
	v_mov_b64_e32 v[104:105], 0
	v_mov_b64_e32 v[114:115], 0
	v_mov_b64_e32 v[116:117], 0
	v_mov_b64_e32 v[118:119], 0
	v_mov_b64_e32 v[120:121], 0
	v_mov_b64_e32 v[126:127], 0
	v_mov_b64_e32 v[128:129], 0
	v_mov_b64_e32 v[130:131], 0
	v_mov_b64_e32 v[132:133], 0
	v_mov_b64_e32 v[166:167], 0
	v_mov_b64_e32 v[168:169], 0
	v_mov_b64_e32 v[170:171], 0
	v_mov_b64_e32 v[172:173], 0
	v_add_u32_e32 v243, 0x10000, v246
	v_add_u32_e32 v244, 0x14000, v246
	v_add_u32_e32 v249, 0x18000, v246
	v_add_u32_e32 v250, 0x1c000, v246
; #define PG8_STAGE(bufoff, gbase, voff) do { _Pragma("unroll") for (int _i = 0; _i < 2; ++_i) \
;         __builtin_amdgcn_global_load_lds((const unsigned*)((const char*)(gbase) + (voff)[_i]), (LAS unsigned*)(lds + (bufoff) + ldsw + _i * 8192), 16, 0, 0); } while (0)
; #define PG8_LDA(dst, b, h) do { _Pragma("unroll") for (int m = 0; m < 4; ++m) _Pragma("unroll") for (int k = 0; k < 2; ++k) dst[m][k] = *(const LAS bf16x8*)(lds + PG8_SA(b, h) + aoff + m * 2048 + k * 1024); } while (0)
; #define PG8_LDB(dst, b, h) do { _Pragma("unroll") for (int n = 0; n < 2; ++n) _Pragma("unroll") for (int k = 0; k < 2; ++k) dst[n][k] = *(const LAS bf16x8*)(lds + PG8_SB(b, h) + boff + n * 2048 + k * 1024); } while (0)
; #define PG8_WAIT_V(n) asm volatile("s_waitcnt vmcnt(" #n ")" ::: "memory")
; #define PG8_BAR __builtin_amdgcn_s_barrier()
; template <class Epi>
; __device__ __forceinline__ void gemm_phase(const int tid, LAS unsigned char* lds, const Gemm g, const StaticOrder& S, const Epi& E) {
;     ...
;         for (int t = 0; t < nt; t += 2) {
;             const bool last = (t == nt - 2);
;             const char* a2 = last ? nA : cA + (size_t)(t + 2) * kstep; const char* b2 = last ? nB : cB + (size_t)(t + 2) * kstep;
;             const char* a3 = a2 + kstep; const char* b3 = b2 + kstep;
;             PG8_LDB(B0, 0, 0); PG8_SCHED; PG8_LDA(At, 0, 0);
;             PG8_WAIT_L(8); PG8_BAR; PG8_WAIT_L(0); PG8_MMA(0, 0, At, B0); PG8_BAR; PG8_SCHED;
;             PG8_LDB(B1, 0, 1); PG8_STAGE(PG8_SB(0, 0), b2, voffB);
;             PG8_BAR; PG8_WAIT_L(0); PG8_MMA(0, 1, At, B1); PG8_BAR;
;             PG8_LDA(At, 0, 1); PG8_STAGE(PG8_SA(0, 0), a2, voffA);
;             PG8_BAR; PG8_WAIT_L(0); PG8_MMA(1, 0, At, B0); PG8_BAR; PG8_SCHED;
;             PG8_STAGE(PG8_SB(0, 1), b2 + hstep, voffB);
;             { const int first_ = __builtin_amdgcn_readfirstlane((ui > 0 && t == 0) ? 1 : 0);
;               if constexpr (Epi::SMIN == 8) asm volatile("s_cmp_eq_u32 %0, 0\n\ts_cbranch_scc1 .Lws_a%=\n\ts_waitcnt vmcnt(14)\n\ts_branch .Lws_b%=\n.Lws_a%=:\n\ts_waitcnt vmcnt(6)\n.Lws_b%=:" :: "s"(first_) : "memory", "scc");
;               else if constexpr (Epi::SMIN == 24) asm volatile("s_cmp_eq_u32 %0, 0\n\ts_cbranch_scc1 .Lws_a%=\n\ts_waitcnt vmcnt(30)\n\ts_branch .Lws_b%=\n.Lws_a%=:\n\ts_waitcnt vmcnt(6)\n.Lws_b%=:" :: "s"(first_) : "memory", "scc");
;               else PG8_WAIT_V(6); }
.LBB0_419:
	s_add_i32 s68, 0, 0x10000
	ds_read_b128 v[106:109], v243
	ds_read_b128 v[110:113], v243 offset:1024
	ds_read_b128 v[122:125], v243 offset:2048
	ds_read_b128 v[134:137], v243 offset:3072
	s_add_i32 s67, s66, 2
	s_cmp_eq_u32 s54, s66
	s_cselect_b32 s15, s9, s61
	s_cselect_b32 s14, s8, s60
	s_cselect_b32 s17, s11, s65
	s_cselect_b32 s16, s10, s64
	ds_read_b128 v[138:141], v248
	ds_read_b128 v[142:145], v248 offset:1024
	ds_read_b128 v[146:149], v248 offset:2048
	ds_read_b128 v[150:153], v248 offset:3072
	ds_read_b128 v[154:157], v248 offset:4096
	ds_read_b128 v[158:161], v248 offset:5120
	ds_read_b128 v[162:165], v248 offset:6144
	ds_read_b128 v[174:177], v248 offset:7168
	s_waitcnt lgkmcnt(8)
	s_barrier
	s_setprio 1
	s_waitcnt lgkmcnt(7)
	v_mfma_f32_16x16x32_bf16 v[170:173], v[106:109], v[138:141], v[170:173]
	v_mfma_f32_16x16x32_bf16 v[166:169], v[122:125], v[138:141], v[166:169]
	s_waitcnt lgkmcnt(5)
	v_mfma_f32_16x16x32_bf16 v[118:121], v[106:109], v[146:149], v[118:121]
	v_mfma_f32_16x16x32_bf16 v[114:117], v[122:125], v[146:149], v[114:117]
	s_waitcnt lgkmcnt(3)
	v_mfma_f32_16x16x32_bf16 v[94:97], v[106:109], v[154:157], v[94:97]
	v_mfma_f32_16x16x32_bf16 v[90:93], v[122:125], v[154:157], v[90:93]
	s_waitcnt lgkmcnt(1)
	v_mfma_f32_16x16x32_bf16 v[78:81], v[106:109], v[162:165], v[78:81]
	v_mfma_f32_16x16x32_bf16 v[74:77], v[122:125], v[162:165], v[74:77]
	v_mfma_f32_16x16x32_bf16 v[170:173], v[110:113], v[142:145], v[170:173]
	v_mfma_f32_16x16x32_bf16 v[166:169], v[134:137], v[142:145], v[166:169]
	v_mfma_f32_16x16x32_bf16 v[118:121], v[110:113], v[150:153], v[118:121]
	v_mfma_f32_16x16x32_bf16 v[114:117], v[134:137], v[150:153], v[114:117]
	v_mfma_f32_16x16x32_bf16 v[94:97], v[110:113], v[158:161], v[94:97]
	v_mfma_f32_16x16x32_bf16 v[90:93], v[134:137], v[158:161], v[90:93]
	s_waitcnt lgkmcnt(0)
	v_mfma_f32_16x16x32_bf16 v[78:81], v[110:113], v[174:177], v[78:81]
	v_mfma_f32_16x16x32_bf16 v[74:77], v[134:137], v[174:177], v[74:77]
	s_setprio 0
	s_barrier
	s_add_i32 s69, 0, 0x14000
	s_add_i32 s68, s68, s28
	s_mov_b32 m0, s68
	ds_read_b128 v[178:181], v244
	ds_read_b128 v[182:185], v244 offset:1024
	ds_read_b128 v[186:189], v244 offset:2048
	ds_read_b128 v[190:193], v244 offset:3072
	global_load_lds_dwordx4 v0, s[16:17]
	s_add_i32 m0, s68, 0x2000
	s_nop 0
	global_load_lds_dwordx4 v194, s[16:17]
	s_barrier
	s_setprio 1
	s_waitcnt lgkmcnt(3)
	v_mfma_f32_16x16x32_bf16 v[130:133], v[178:181], v[138:141], v[130:133]
	s_waitcnt lgkmcnt(1)
	v_mfma_f32_16x16x32_bf16 v[126:129], v[186:189], v[138:141], v[126:129]
	v_mfma_f32_16x16x32_bf16 v[102:105], v[178:181], v[146:149], v[102:105]
	v_mfma_f32_16x16x32_bf16 v[98:101], v[186:189], v[146:149], v[98:101]
	v_mfma_f32_16x16x32_bf16 v[86:89], v[178:181], v[154:157], v[86:89]
	v_mfma_f32_16x16x32_bf16 v[82:85], v[186:189], v[154:157], v[82:85]
	v_mfma_f32_16x16x32_bf16 v[70:73], v[178:181], v[162:165], v[70:73]
	v_mfma_f32_16x16x32_bf16 v[66:69], v[186:189], v[162:165], v[66:69]
	v_mfma_f32_16x16x32_bf16 v[130:133], v[182:185], v[142:145], v[130:133]
	s_waitcnt lgkmcnt(0)
	v_mfma_f32_16x16x32_bf16 v[126:129], v[190:193], v[142:145], v[126:129]
	v_mfma_f32_16x16x32_bf16 v[102:105], v[182:185], v[150:153], v[102:105]
	v_mfma_f32_16x16x32_bf16 v[98:101], v[190:193], v[150:153], v[98:101]
	v_mfma_f32_16x16x32_bf16 v[86:89], v[182:185], v[158:161], v[86:89]
	v_mfma_f32_16x16x32_bf16 v[82:85], v[190:193], v[158:161], v[82:85]
	v_mfma_f32_16x16x32_bf16 v[70:73], v[182:185], v[174:177], v[70:73]
	v_mfma_f32_16x16x32_bf16 v[66:69], v[190:193], v[174:177], v[66:69]
	s_setprio 0
	s_mov_b32 m0, s36
	s_barrier
	ds_read_b128 v[138:141], v248 offset:16384
	ds_read_b128 v[142:145], v248 offset:17408
	ds_read_b128 v[146:149], v248 offset:18432
	ds_read_b128 v[150:153], v248 offset:19456
	ds_read_b128 v[154:157], v248 offset:20480
	ds_read_b128 v[158:161], v248 offset:21504
	ds_read_b128 v[162:165], v248 offset:22528
	ds_read_b128 v[174:177], v248 offset:23552
	global_load_lds_dwordx4 v198, s[14:15]
	s_mov_b32 m0, s37
	s_nop 0
	global_load_lds_dwordx4 v196, s[14:15]
	s_barrier
	s_setprio 1
	s_waitcnt lgkmcnt(7)
	v_mfma_f32_16x16x32_bf16 v[62:65], v[106:109], v[138:141], v[62:65]
	v_mfma_f32_16x16x32_bf16 v[58:61], v[122:125], v[138:141], v[58:61]
	s_waitcnt lgkmcnt(5)
	v_mfma_f32_16x16x32_bf16 v[46:49], v[106:109], v[146:149], v[46:49]
	v_mfma_f32_16x16x32_bf16 v[42:45], v[122:125], v[146:149], v[42:45]
	s_waitcnt lgkmcnt(3)
	v_mfma_f32_16x16x32_bf16 v[30:33], v[106:109], v[154:157], v[30:33]
	v_mfma_f32_16x16x32_bf16 v[26:29], v[122:125], v[154:157], v[26:29]
	s_waitcnt lgkmcnt(1)
	v_mfma_f32_16x16x32_bf16 v[14:17], v[106:109], v[162:165], v[14:17]
	v_mfma_f32_16x16x32_bf16 v[10:13], v[122:125], v[162:165], v[10:13]
	v_mfma_f32_16x16x32_bf16 v[62:65], v[110:113], v[142:145], v[62:65]
	v_mfma_f32_16x16x32_bf16 v[58:61], v[134:137], v[142:145], v[58:61]
	v_mfma_f32_16x16x32_bf16 v[46:49], v[110:113], v[150:153], v[46:49]
	v_mfma_f32_16x16x32_bf16 v[42:45], v[134:137], v[150:153], v[42:45]
	v_mfma_f32_16x16x32_bf16 v[30:33], v[110:113], v[158:161], v[30:33]
	v_mfma_f32_16x16x32_bf16 v[26:29], v[134:137], v[158:161], v[26:29]
	s_waitcnt lgkmcnt(0)
	v_mfma_f32_16x16x32_bf16 v[14:17], v[110:113], v[174:177], v[14:17]
	v_mfma_f32_16x16x32_bf16 v[10:13], v[134:137], v[174:177], v[10:13]
	s_setprio 0
	s_barrier
	s_add_u32 s16, s16, s26
	s_addc_u32 s17, s17, 0
	s_add_i32 s68, s69, s28
	s_mov_b32 m0, s68
	s_nop 0
	global_load_lds_dwordx4 v0, s[16:17]
	s_add_i32 m0, s68, 0x2000
	s_cmp_eq_u32 s66, 0
	global_load_lds_dwordx4 v194, s[16:17]
	s_cselect_b64 s[16:17], -1, 0
	s_and_b64 s[16:17], s[12:13], s[16:17]
	v_cndmask_b32_e64 v106, 0, 1, s[16:17]
	s_nop 0
	v_readfirstlane_b32 s16, v106
	s_and_b32 s16, s16, 1
	s_cmp_eq_u32 s16, 0
	s_cbranch_scc1 .Lws_a0
	s_waitcnt vmcnt(30)
	s_branch .Lws_b0

; #define PG8_STAGE(bufoff, gbase, voff) do { _Pragma("unroll") for (int _i = 0; _i < 2; ++_i) \
;         __builtin_amdgcn_global_load_lds((const unsigned*)((const char*)(gbase) + (voff)[_i]), (LAS unsigned*)(lds + (bufoff) + ldsw + _i * 8192), 16, 0, 0); } while (0)
; #define PG8_LDA(dst, b, h) do { _Pragma("unroll") for (int m = 0; m < 4; ++m) _Pragma("unroll") for (int k = 0; k < 2; ++k) dst[m][k] = *(const LAS bf16x8*)(lds + PG8_SA(b, h) + aoff + m * 2048 + k * 1024); } while (0)
; #define PG8_LDB(dst, b, h) do { _Pragma("unroll") for (int n = 0; n < 2; ++n) _Pragma("unroll") for (int k = 0; k < 2; ++k) dst[n][k] = *(const LAS bf16x8*)(lds + PG8_SB(b, h) + boff + n * 2048 + k * 1024); } while (0)
; #define PG8_MMA(ai, bj, At, Bt) do { __builtin_amdgcn_s_setprio(1); _Pragma("unroll") for (int m = 0; m < 4; ++m) _Pragma("unroll") for (int n = 0; n < 2; ++n) _Pragma("unroll") for (int k = 0; k < 2; ++k) \
;         acc[ai][bj][m][n] = __builtin_amdgcn_mfma_f32_16x16x32_bf16(Bt[n][k], At[m][k], acc[ai][bj][m][n], 0, 0, 0); __builtin_amdgcn_s_setprio(0); } while (0)
; #define PG8_WAIT_L(n) asm volatile("s_waitcnt lgkmcnt(" #n ")" ::: "memory")
; #define PG8_BAR __builtin_amdgcn_s_barrier()
; #define PG8_SCHED __builtin_amdgcn_sched_barrier(0)
; template <class Epi>
; __device__ __forceinline__ void gemm_phase(const int tid, LAS unsigned char* lds, const Gemm g, const StaticOrder& S, const Epi& E) {
;     ...
;             PG8_BAR; PG8_MMA(1, 1, At, B1); PG8_BAR;
;             PG8_LDB(B0, 1, 0); PG8_SCHED; PG8_LDA(At, 1, 0); PG8_STAGE(PG8_SA(0, 1), a2 + hstep, voffA);
;             PG8_WAIT_L(8); PG8_BAR; PG8_WAIT_L(0); PG8_MMA(0, 0, At, B0); PG8_BAR; PG8_SCHED;
;             PG8_LDB(B1, 1, 1); PG8_STAGE(PG8_SB(1, 0), b3, voffB);
;             PG8_BAR; PG8_WAIT_L(0); PG8_MMA(0, 1, At, B1); PG8_BAR;
;             PG8_LDA(At, 1, 1); PG8_STAGE(PG8_SA(1, 0), a3, voffA);
;             PG8_BAR; PG8_WAIT_L(0); PG8_MMA(1, 0, At, B0); PG8_BAR; PG8_SCHED;
.Lws_b0:
	s_barrier
	s_setprio 1
	v_mfma_f32_16x16x32_bf16 v[54:57], v[178:181], v[138:141], v[54:57]
	v_mfma_f32_16x16x32_bf16 v[50:53], v[186:189], v[138:141], v[50:53]
	v_mfma_f32_16x16x32_bf16 v[38:41], v[178:181], v[146:149], v[38:41]
	v_mfma_f32_16x16x32_bf16 v[34:37], v[186:189], v[146:149], v[34:37]
	v_mfma_f32_16x16x32_bf16 v[22:25], v[178:181], v[154:157], v[22:25]
	v_mfma_f32_16x16x32_bf16 v[18:21], v[186:189], v[154:157], v[18:21]
	v_mfma_f32_16x16x32_bf16 v[6:9], v[178:181], v[162:165], v[6:9]
	v_mfma_f32_16x16x32_bf16 v[2:5], v[186:189], v[162:165], v[2:5]
	v_mfma_f32_16x16x32_bf16 v[54:57], v[182:185], v[142:145], v[54:57]
	v_mfma_f32_16x16x32_bf16 v[50:53], v[190:193], v[142:145], v[50:53]
	v_mfma_f32_16x16x32_bf16 v[38:41], v[182:185], v[150:153], v[38:41]
	v_mfma_f32_16x16x32_bf16 v[34:37], v[190:193], v[150:153], v[34:37]
	v_mfma_f32_16x16x32_bf16 v[22:25], v[182:185], v[158:161], v[22:25]
	v_mfma_f32_16x16x32_bf16 v[18:21], v[190:193], v[158:161], v[18:21]
	v_mfma_f32_16x16x32_bf16 v[6:9], v[182:185], v[174:177], v[6:9]
	v_mfma_f32_16x16x32_bf16 v[2:5], v[190:193], v[174:177], v[2:5]
	s_setprio 0
	s_add_i32 s16, 0, 0x18000
	s_barrier
	ds_read_b128 v[106:109], v249
	ds_read_b128 v[110:113], v249 offset:1024
	ds_read_b128 v[122:125], v249 offset:2048
	ds_read_b128 v[134:137], v249 offset:3072
	s_add_u32 s14, s14, s26
	s_addc_u32 s15, s15, 0
	s_mov_b32 m0, s38
	ds_read_b128 v[138:141], v248 offset:32768
	ds_read_b128 v[142:145], v248 offset:33792
	ds_read_b128 v[146:149], v248 offset:34816
	ds_read_b128 v[150:153], v248 offset:35840
	ds_read_b128 v[154:157], v248 offset:36864
	ds_read_b128 v[158:161], v248 offset:37888
	ds_read_b128 v[162:165], v248 offset:38912
	ds_read_b128 v[174:177], v248 offset:39936
	global_load_lds_dwordx4 v198, s[14:15]
	s_mov_b32 m0, s39
	s_nop 0
	global_load_lds_dwordx4 v196, s[14:15]
	s_waitcnt lgkmcnt(8)
	s_barrier
	s_setprio 1
	s_waitcnt lgkmcnt(7)
	v_mfma_f32_16x16x32_bf16 v[170:173], v[106:109], v[138:141], v[170:173]
	v_mfma_f32_16x16x32_bf16 v[166:169], v[122:125], v[138:141], v[166:169]
	s_waitcnt lgkmcnt(5)
	v_mfma_f32_16x16x32_bf16 v[118:121], v[106:109], v[146:149], v[118:121]
	v_mfma_f32_16x16x32_bf16 v[114:117], v[122:125], v[146:149], v[114:117]
	s_waitcnt lgkmcnt(3)
	v_mfma_f32_16x16x32_bf16 v[94:97], v[106:109], v[154:157], v[94:97]
	v_mfma_f32_16x16x32_bf16 v[90:93], v[122:125], v[154:157], v[90:93]
	s_waitcnt lgkmcnt(1)
	v_mfma_f32_16x16x32_bf16 v[78:81], v[106:109], v[162:165], v[78:81]
	v_mfma_f32_16x16x32_bf16 v[74:77], v[122:125], v[162:165], v[74:77]
	v_mfma_f32_16x16x32_bf16 v[170:173], v[110:113], v[142:145], v[170:173]
	v_mfma_f32_16x16x32_bf16 v[166:169], v[134:137], v[142:145], v[166:169]
	v_mfma_f32_16x16x32_bf16 v[118:121], v[110:113], v[150:153], v[118:121]
	v_mfma_f32_16x16x32_bf16 v[114:117], v[134:137], v[150:153], v[114:117]
	v_mfma_f32_16x16x32_bf16 v[94:97], v[110:113], v[158:161], v[94:97]
	v_mfma_f32_16x16x32_bf16 v[90:93], v[134:137], v[158:161], v[90:93]
	s_waitcnt lgkmcnt(0)
	v_mfma_f32_16x16x32_bf16 v[78:81], v[110:113], v[174:177], v[78:81]
	v_mfma_f32_16x16x32_bf16 v[74:77], v[134:137], v[174:177], v[74:77]
	s_setprio 0
	s_barrier
	s_add_i32 s14, 0, 0x1c000
	s_add_i32 s15, s16, s28
	s_cmp_eq_u32 s54, s66
	s_cselect_b32 s17, s11, s65
	s_cselect_b32 s16, s10, s64
	s_cselect_b32 s69, s9, s61
	s_cselect_b32 s68, s8, s60
	s_add_i32 m0, s15, 0xffffff80
	ds_read_b128 v[178:181], v250
	ds_read_b128 v[182:185], v250 offset:1024
	ds_read_b128 v[186:189], v250 offset:2048
	ds_read_b128 v[190:193], v250 offset:3072
	global_load_lds_dwordx4 v0, s[16:17] offset:128
	s_add_i32 m0, s15, 0x1f80
	s_nop 0
	global_load_lds_dwordx4 v194, s[16:17] offset:128
	s_barrier
	s_setprio 1
	s_waitcnt lgkmcnt(3)
	v_mfma_f32_16x16x32_bf16 v[130:133], v[178:181], v[138:141], v[130:133]
	s_waitcnt lgkmcnt(1)
	v_mfma_f32_16x16x32_bf16 v[126:129], v[186:189], v[138:141], v[126:129]
	v_mfma_f32_16x16x32_bf16 v[102:105], v[178:181], v[146:149], v[102:105]
	v_mfma_f32_16x16x32_bf16 v[98:101], v[186:189], v[146:149], v[98:101]
	v_mfma_f32_16x16x32_bf16 v[86:89], v[178:181], v[154:157], v[86:89]
	v_mfma_f32_16x16x32_bf16 v[82:85], v[186:189], v[154:157], v[82:85]
	v_mfma_f32_16x16x32_bf16 v[70:73], v[178:181], v[162:165], v[70:73]
	v_mfma_f32_16x16x32_bf16 v[66:69], v[186:189], v[162:165], v[66:69]
	v_mfma_f32_16x16x32_bf16 v[130:133], v[182:185], v[142:145], v[130:133]
	s_waitcnt lgkmcnt(0)
	v_mfma_f32_16x16x32_bf16 v[126:129], v[190:193], v[142:145], v[126:129]
	v_mfma_f32_16x16x32_bf16 v[102:105], v[182:185], v[150:153], v[102:105]
	v_mfma_f32_16x16x32_bf16 v[98:101], v[190:193], v[150:153], v[98:101]
	v_mfma_f32_16x16x32_bf16 v[86:89], v[182:185], v[158:161], v[86:89]
	v_mfma_f32_16x16x32_bf16 v[82:85], v[190:193], v[158:161], v[82:85]
	v_mfma_f32_16x16x32_bf16 v[70:73], v[182:185], v[174:177], v[70:73]
	v_mfma_f32_16x16x32_bf16 v[66:69], v[190:193], v[174:177], v[66:69]
	s_setprio 0
	s_add_i32 m0, s46, 0xffffff80
	s_barrier
	ds_read_b128 v[138:141], v248 offset:49152
	ds_read_b128 v[142:145], v248 offset:50176
	ds_read_b128 v[146:149], v248 offset:51200
	ds_read_b128 v[150:153], v248 offset:52224
	ds_read_b128 v[154:157], v248 offset:53248
	ds_read_b128 v[158:161], v248 offset:54272
	ds_read_b128 v[162:165], v248 offset:55296
	ds_read_b128 v[174:177], v248 offset:56320
	global_load_lds_dwordx4 v198, s[68:69] offset:128
	s_add_i32 m0, s47, 0xffffff80
	s_nop 0
	global_load_lds_dwordx4 v196, s[68:69] offset:128
	s_barrier
; #define PG8_STAGE(bufoff, gbase, voff) do { _Pragma("unroll") for (int _i = 0; _i < 2; ++_i) \
;         __builtin_amdgcn_global_load_lds((const unsigned*)((const char*)(gbase) + (voff)[_i]), (LAS unsigned*)(lds + (bufoff) + ldsw + _i * 8192), 16, 0, 0); } while (0)
; #define PG8_MMA(ai, bj, At, Bt) do { __builtin_amdgcn_s_setprio(1); _Pragma("unroll") for (int m = 0; m < 4; ++m) _Pragma("unroll") for (int n = 0; n < 2; ++n) _Pragma("unroll") for (int k = 0; k < 2; ++k) \
;         acc[ai][bj][m][n] = __builtin_amdgcn_mfma_f32_16x16x32_bf16(Bt[n][k], At[m][k], acc[ai][bj][m][n], 0, 0, 0); __builtin_amdgcn_s_setprio(0); } while (0)
; #define PG8_WAIT_V(n) asm volatile("s_waitcnt vmcnt(" #n ")" ::: "memory")
; #define PG8_WAIT_L(n) asm volatile("s_waitcnt lgkmcnt(" #n ")" ::: "memory")
; #define PG8_BAR __builtin_amdgcn_s_barrier()
; #define PG8_SCHED __builtin_amdgcn_sched_barrier(0)
; template <class Epi>
; __device__ __forceinline__ void gemm_phase(const int tid, LAS unsigned char* lds, const Gemm g, const StaticOrder& S, const Epi& E) {
;     ...
;             PG8_BAR; PG8_WAIT_L(0); PG8_MMA(1, 0, At, B0); PG8_BAR; PG8_SCHED;
;             PG8_STAGE(PG8_SB(1, 1), b3 + hstep, voffB);
;             PG8_WAIT_V(6); PG8_BAR; PG8_STAGE(PG8_SA(1, 1), a3 + hstep, voffA);
;             PG8_MMA(1, 1, At, B1); PG8_BAR;
;         }
	s_setprio 1
	s_waitcnt lgkmcnt(7)
	v_mfma_f32_16x16x32_bf16 v[62:65], v[106:109], v[138:141], v[62:65]
	v_mfma_f32_16x16x32_bf16 v[58:61], v[122:125], v[138:141], v[58:61]
	s_waitcnt lgkmcnt(5)
	v_mfma_f32_16x16x32_bf16 v[46:49], v[106:109], v[146:149], v[46:49]
	v_mfma_f32_16x16x32_bf16 v[42:45], v[122:125], v[146:149], v[42:45]
	s_waitcnt lgkmcnt(3)
	v_mfma_f32_16x16x32_bf16 v[30:33], v[106:109], v[154:157], v[30:33]
	v_mfma_f32_16x16x32_bf16 v[26:29], v[122:125], v[154:157], v[26:29]
	s_waitcnt lgkmcnt(1)
	v_mfma_f32_16x16x32_bf16 v[14:17], v[106:109], v[162:165], v[14:17]
	v_mfma_f32_16x16x32_bf16 v[10:13], v[122:125], v[162:165], v[10:13]
	v_mfma_f32_16x16x32_bf16 v[62:65], v[110:113], v[142:145], v[62:65]
	v_mfma_f32_16x16x32_bf16 v[58:61], v[134:137], v[142:145], v[58:61]
	v_mfma_f32_16x16x32_bf16 v[46:49], v[110:113], v[150:153], v[46:49]
	v_mfma_f32_16x16x32_bf16 v[42:45], v[134:137], v[150:153], v[42:45]
	v_mfma_f32_16x16x32_bf16 v[30:33], v[110:113], v[158:161], v[30:33]
	v_mfma_f32_16x16x32_bf16 v[26:29], v[134:137], v[158:161], v[26:29]
	s_waitcnt lgkmcnt(0)
	v_mfma_f32_16x16x32_bf16 v[14:17], v[110:113], v[174:177], v[14:17]
	v_mfma_f32_16x16x32_bf16 v[10:13], v[134:137], v[174:177], v[10:13]
	s_setprio 0
	s_barrier
	s_add_i32 s14, s14, s28
	s_add_u32 s16, s16, s26
	s_addc_u32 s17, s17, 0
	s_add_i32 m0, s14, 0xffffff80
	s_nop 0
	global_load_lds_dwordx4 v0, s[16:17] offset:128
	s_add_i32 m0, s14, 0x1f80
	s_nop 0
	global_load_lds_dwordx4 v194, s[16:17] offset:128
	s_add_u32 s68, s68, s26
	s_addc_u32 s69, s69, 0
	s_add_i32 m0, s48, 0xffffff80
	s_waitcnt vmcnt(6)
	s_barrier
	global_load_lds_dwordx4 v198, s[68:69] offset:128
	s_add_i32 m0, s49, 0xffffff80
	s_nop 0
	global_load_lds_dwordx4 v196, s[68:69] offset:128
	s_setprio 1
	v_mfma_f32_16x16x32_bf16 v[54:57], v[178:181], v[138:141], v[54:57]
	v_mfma_f32_16x16x32_bf16 v[50:53], v[186:189], v[138:141], v[50:53]
	v_mfma_f32_16x16x32_bf16 v[38:41], v[178:181], v[146:149], v[38:41]
	v_mfma_f32_16x16x32_bf16 v[34:37], v[186:189], v[146:149], v[34:37]
	v_mfma_f32_16x16x32_bf16 v[22:25], v[178:181], v[154:157], v[22:25]
	v_mfma_f32_16x16x32_bf16 v[18:21], v[186:189], v[154:157], v[18:21]
	v_mfma_f32_16x16x32_bf16 v[6:9], v[178:181], v[162:165], v[6:9]
	v_mfma_f32_16x16x32_bf16 v[2:5], v[186:189], v[162:165], v[2:5]
	v_mfma_f32_16x16x32_bf16 v[54:57], v[182:185], v[142:145], v[54:57]
	v_mfma_f32_16x16x32_bf16 v[50:53], v[190:193], v[142:145], v[50:53]
	v_mfma_f32_16x16x32_bf16 v[38:41], v[182:185], v[150:153], v[38:41]
	v_mfma_f32_16x16x32_bf16 v[34:37], v[190:193], v[150:153], v[34:37]
	v_mfma_f32_16x16x32_bf16 v[22:25], v[182:185], v[158:161], v[22:25]
	v_mfma_f32_16x16x32_bf16 v[18:21], v[190:193], v[158:161], v[18:21]
	v_mfma_f32_16x16x32_bf16 v[6:9], v[182:185], v[174:177], v[6:9]
	v_mfma_f32_16x16x32_bf16 v[2:5], v[190:193], v[174:177], v[2:5]
	s_setprio 0
	s_add_u32 s60, s60, 0x100
	s_addc_u32 s61, s61, 0
	s_add_u32 s64, s64, 0x100
	s_addc_u32 s65, s65, 0
	s_cmp_ge_u32 s67, s51
	s_mov_b32 s66, s67
	s_barrier
	s_cbranch_scc0 .LBB0_419
; __device__ __forceinline__ unsigned cvtpk(float lo, float hi) { unsigned r; asm volatile("v_cvt_pk_bf16_f32 %0, %1, %2" : "=v"(r) : "v"(lo), "v"(hi)); return r; }
; __device__ __forceinline__ float bflo(unsigned w) { return __uint_as_float(w << 16); }
; __device__ __forceinline__ float bfhi(unsigned w) { return __uint_as_float(w & 0xffff0000u); }
;     __device__ __forceinline__ void operator()(const AccT& acc, const pg8::Unit& u, int wr, int wc, int fr, int fq, pg8::RsCache& rsc) const {
;         const int row0 = u.pm * 256 + wr * 64 + fr, col0 = u.pn * 256 + wc * 32 + 8 * fq;
;         u32x4 xv[2][4][2];
; #pragma unroll
;         for (int ai = 0; ai < 2; ++ai)
; #pragma unroll
;             for (int m = 0; m < 4; ++m)
; #pragma unroll
;                 for (int bj = 0; bj < 2; ++bj) xv[ai][m][bj] = *(const u32x4*)(XB + (size_t)(row0 + ai * 128 + m * 16) * DM + col0 + bj * 128);
;         asm volatile("" ::: "memory");
; #pragma unroll
;         for (int ai = 0; ai < 2; ++ai) {
; #pragma unroll
;             for (int m = 0; m < 4; ++m) {
;                 const int row = row0 + ai * 128 + m * 16; float ss = 0.f;
; #pragma unroll
;                 for (int bj = 0; bj < 2; ++bj) {
;                     const u32x4 xx = xv[ai][m][bj]; const f32x4 a0 = acc[ai][bj][m][0] * scale, a1 = acc[ai][bj][m][1] * scale;
;                     const float y0 = bflo(xx.x) + a0[0], y1 = bfhi(xx.x) + a0[1], y2 = bflo(xx.y) + a0[2], y3 = bfhi(xx.y) + a0[3];
;                     const float y4 = bflo(xx.z) + a1[0], y5 = bfhi(xx.z) + a1[1], y6 = bflo(xx.w) + a1[2], y7 = bfhi(xx.w) + a1[3];
;                     u32x4 w; w.x = cvtpk(y0, y1); w.y = cvtpk(y2, y3); w.z = cvtpk(y4, y5); w.w = cvtpk(y6, y7);
;                     *(u32x4*)(XB + (size_t)row * DM + col0 + bj * 128) = w;
;                     ss += (y0 * y0 + y1 * y1) + (y2 * y2 + y3 * y3) + (y4 * y4 + y5 * y5) + (y6 * y6 + y7 * y7);
;                 }
;                 ss = xadd<16>(ss); ss = xadd<32>(ss);
;                 if (fq == 0) ssq_next[(size_t)row * 32 + u.pn * 4 + wc] = ss;
;             }
;         }
;     }
	v_lshl_or_b32 v206, s30, 8, v247
	v_lshl_add_u32 v234, s59, 8, v245
	v_ashrrev_i32_e32 v207, 31, v206
	v_lshlrev_b64 v[236:237], 1, v[206:207]
	v_ashrrev_i32_e32 v235, 31, v234
	v_lshl_add_u64 v[106:107], s[62:63], 0, v[236:237]
	v_lshlrev_b64 v[238:239], 12, v[234:235]
	v_lshl_add_u64 v[108:109], v[106:107], 0, v[238:239]
	global_load_dwordx4 v[190:193], v[108:109], off
	global_load_dwordx4 v[186:189], v[108:109], off offset:256
	v_or_b32_e32 v230, 16, v234
	v_ashrrev_i32_e32 v231, 31, v230
	v_or_b32_e32 v226, 32, v234
	v_lshlrev_b64 v[232:233], 12, v[230:231]
	v_ashrrev_i32_e32 v227, 31, v226
	v_or_b32_e32 v222, 48, v234
	v_lshl_add_u64 v[108:109], v[106:107], 0, v[232:233]
	v_lshlrev_b64 v[228:229], 12, v[226:227]
	v_ashrrev_i32_e32 v223, 31, v222
	v_add_u32_e32 v218, 0x80, v234
	global_load_dwordx4 v[182:185], v[108:109], off
	global_load_dwordx4 v[178:181], v[108:109], off offset:256
	v_lshl_add_u64 v[108:109], v[106:107], 0, v[228:229]
	v_lshlrev_b64 v[224:225], 12, v[222:223]
	v_ashrrev_i32_e32 v219, 31, v218
	v_add_u32_e32 v214, 0x90, v234
	global_load_dwordx4 v[174:177], v[108:109], off
	global_load_dwordx4 v[162:165], v[108:109], off offset:256
	v_lshl_add_u64 v[108:109], v[106:107], 0, v[224:225]
	v_lshlrev_b64 v[220:221], 12, v[218:219]
	v_ashrrev_i32_e32 v215, 31, v214
	v_add_u32_e32 v210, 0xa0, v234
	v_add_u32_e32 v204, 0xb0, v234
	global_load_dwordx4 v[158:161], v[108:109], off
	global_load_dwordx4 v[154:157], v[108:109], off offset:256
	v_lshl_add_u64 v[108:109], v[106:107], 0, v[220:221]
	v_lshlrev_b64 v[216:217], 12, v[214:215]
	v_ashrrev_i32_e32 v211, 31, v210
	v_ashrrev_i32_e32 v205, 31, v204
	global_load_dwordx4 v[150:153], v[108:109], off
	global_load_dwordx4 v[146:149], v[108:109], off offset:256
	v_lshl_add_u64 v[108:109], v[106:107], 0, v[216:217]
	v_lshlrev_b64 v[212:213], 12, v[210:211]
	v_lshlrev_b64 v[208:209], 12, v[204:205]
	global_load_dwordx4 v[142:145], v[108:109], off
	global_load_dwordx4 v[138:141], v[108:109], off offset:256
	v_lshl_add_u64 v[108:109], v[106:107], 0, v[212:213]
	v_lshl_add_u64 v[106:107], v[106:107], 0, v[208:209]
	global_load_dwordx4 v[134:137], v[108:109], off
	global_load_dwordx4 v[122:125], v[108:109], off offset:256
	global_load_dwordx4 v[110:113], v[106:107], off
	s_nop 0
	global_load_dwordx4 v[106:109], v[106:107], off offset:256
	v_pk_mul_f32 v[170:171], v[202:203], v[170:171]
	v_mov_b32_e32 v201, v200
	v_pk_mul_f32 v[172:173], v[200:201], v[172:173]
	v_pk_mul_f32 v[166:167], v[202:203], v[166:167]
	v_pk_mul_f32 v[168:169], v[200:201], v[168:169]
	v_pk_mul_f32 v[130:131], v[202:203], v[130:131]
	v_pk_mul_f32 v[132:133], v[200:201], v[132:133]
	v_pk_mul_f32 v[126:127], v[202:203], v[126:127]
	v_pk_mul_f32 v[128:129], v[200:201], v[128:129]
	s_lshl_b32 s12, s30, 2
	s_ashr_i32 s13, s12, 31
	s_waitcnt vmcnt(0)
	v_lshlrev_b32_e32 v240, 16, v190
	v_add_f32_e32 v240, v170, v240
	v_and_b32_e32 v170, 0xffff0000, v190
	v_add_f32_e32 v190, v171, v170
	v_lshlrev_b32_e32 v170, 16, v191
	v_add_f32_e32 v172, v172, v170
	v_and_b32_e32 v170, 0xffff0000, v191
	v_add_f32_e32 v173, v173, v170
	v_lshlrev_b32_e32 v170, 16, v192
	v_add_f32_e32 v191, v166, v170
	v_and_b32_e32 v166, 0xffff0000, v192
	v_add_f32_e32 v192, v167, v166
	v_lshlrev_b32_e32 v166, 16, v193
	v_add_f32_e32 v241, v168, v166
	v_and_b32_e32 v166, 0xffff0000, v193
	v_lshl_add_u64 v[170:171], s[62:63], 0, v[238:239]
	v_add_f32_e32 v193, v169, v166
	v_cvt_pk_bf16_f32 v166, v240, v190
	v_cvt_pk_bf16_f32 v167, v172, v173
	v_lshl_add_u64 v[170:171], v[170:171], 0, v[236:237]
	v_cvt_pk_bf16_f32 v168, v191, v192
	v_cvt_pk_bf16_f32 v169, v241, v193
	global_store_dwordx4 v[170:171], v[166:169], off
	s_nop 1
	v_mul_f32_e32 v166, v190, v190
	v_mul_f32_e32 v167, v173, v173
	v_fmac_f32_e32 v166, v240, v240
	v_fmac_f32_e32 v167, v172, v172
	v_add_f32_e32 v166, v166, v167
	v_mul_f32_e32 v167, v192, v192
	v_fmac_f32_e32 v167, v191, v191
	v_add_f32_e32 v166, v167, v166
	v_mul_f32_e32 v167, v193, v193
	v_fmac_f32_e32 v167, v241, v241
	v_add_f32_e32 v166, v167, v166
	v_lshlrev_b32_e32 v167, 16, v186
	v_add_f32_e32 v130, v130, v167
	v_and_b32_e32 v167, 0xffff0000, v186
	v_add_f32_e32 v131, v131, v167
	v_lshlrev_b32_e32 v167, 16, v187
	v_add_f32_e32 v132, v132, v167
	v_and_b32_e32 v167, 0xffff0000, v187
	v_add_f32_e32 v133, v133, v167
	v_lshlrev_b32_e32 v167, 16, v188
	v_add_f32_e32 v167, v126, v167
	v_and_b32_e32 v126, 0xffff0000, v188
	v_add_f32_e32 v168, v127, v126
	v_lshlrev_b32_e32 v126, 16, v189
	v_add_f32_e32 v169, v128, v126
	v_and_b32_e32 v126, 0xffff0000, v189
	v_add_f32_e32 v172, v129, v126
	v_cvt_pk_bf16_f32 v126, v130, v131
	v_cvt_pk_bf16_f32 v127, v132, v133
	v_cvt_pk_bf16_f32 v128, v167, v168
	v_cvt_pk_bf16_f32 v129, v169, v172
	global_store_dwordx4 v[170:171], v[126:129], off offset:256
	s_nop 1
	v_mul_f32_e32 v126, v131, v131
	v_mul_f32_e32 v127, v133, v133
	v_fmac_f32_e32 v126, v130, v130
	v_fmac_f32_e32 v127, v132, v132
	v_add_f32_e32 v126, v126, v127
	v_mul_f32_e32 v127, v168, v168
	v_fmac_f32_e32 v127, v167, v167
	v_add_f32_e32 v126, v127, v126
	v_mul_f32_e32 v127, v172, v172
	v_fmac_f32_e32 v127, v169, v169
	v_add_f32_e32 v126, v127, v126
	v_add_f32_e32 v126, v166, v126
	ds_swizzle_b32 v127, v126 offset:swizzle(SWAP,16)
	s_waitcnt lgkmcnt(0)
	v_add_f32_e32 v126, v126, v127
	v_mov_b32_e32 v127, v126
	s_nop 1
	v_permlane32_swap_b32_e32 v126, v127
	s_and_saveexec_b64 s[14:15], s[4:5]
	s_cbranch_execz .LBB0_422
	v_lshlrev_b64 v[128:129], 7, v[234:235]
	v_lshl_add_u64 v[128:129], s[0:1], 0, v[128:129]
	v_lshl_add_u64 v[128:129], s[12:13], 2, v[128:129]
	s_lshl_b32 s30, s50, 2
	v_lshl_add_u64 v[128:129], v[128:129], 0, s[30:31]
	v_add_f32_e32 v126, v126, v127
	global_store_dword v[128:129], v126, off

; #define PG8_LDA(dst, b, h) do { _Pragma("unroll") for (int m = 0; m < 4; ++m) _Pragma("unroll") for (int k = 0; k < 2; ++k) dst[m][k] = *(const LAS bf16x8*)(lds + PG8_SA(b, h) + aoff + m * 2048 + k * 1024); } while (0)
; #define PG8_LDB(dst, b, h) do { _Pragma("unroll") for (int n = 0; n < 2; ++n) _Pragma("unroll") for (int k = 0; k < 2; ++k) dst[n][k] = *(const LAS bf16x8*)(lds + PG8_SB(b, h) + boff + n * 2048 + k * 1024); } while (0)
; #define PG8_SCHED __builtin_amdgcn_sched_barrier(0)
; template <class Epi>
; __device__ __forceinline__ void gemm_phase(const int tid, LAS unsigned char* lds, const Gemm g, const StaticOrder& S, const Epi& E) {
;     ...
;         const bool has_next = S.next(ui + 1, nxt);
;         const char* nA = has_next ? (const char*)g.A + (size_t)nxt.pm * tstep : cA; const char* nB = has_next ? (const char*)g.Bt + (size_t)nxt.pn * tstep : cB;
;         for (int t = 0; t < nt; t += 2) {
;             const bool last = (t == nt - 2);
;             const char* a2 = last ? nA : cA + (size_t)(t + 2) * kstep; const char* b2 = last ? nB : cB + (size_t)(t + 2) * kstep;
;             const char* a3 = a2 + kstep; const char* b3 = b2 + kstep;
;             PG8_LDB(B0, 0, 0); PG8_SCHED; PG8_LDA(At, 0, 0);
;     ...
; #pragma unroll
;         for (int a = 0; a < 2; ++a)
; #pragma unroll
;             for (int b = 0; b < 2; ++b)
; #pragma unroll
;                 for (int m = 0; m < 4; ++m)
; #pragma unroll
;                     for (int n = 0; n < 2; ++n) acc[a][b][m][n] = (f32x4){0.f, 0.f, 0.f, 0.f};
.LBB0_447:
	v_mov_b64_e32 v[2:3], 0x1020
	s_ashr_i32 s13, s12, 31
	v_cmp_lt_i64_e32 vcc, s[14:15], v[2:3]
	s_lshl_b64 s[14:15], s[12:13], 20
	s_add_u32 s14, s62, s14
	s_addc_u32 s15, s63, s15
	s_and_b64 s[16:17], vcc, exec
	s_cselect_b32 s13, s15, s37
	s_cselect_b32 s57, s14, s36
	s_ashr_i32 s11, s10, 31
	s_lshl_b64 s[16:17], s[10:11], 20
	s_add_u32 s16, s26, s16
	s_addc_u32 s17, s27, s17
	s_and_b64 s[58:59], vcc, exec
	s_cselect_b32 s11, s17, s25
	s_cselect_b32 s58, s16, s24
	s_cmp_lg_u32 s22, 0
	s_cselect_b64 s[22:23], -1, 0
	s_add_u32 s59, s36, 0x100
	s_addc_u32 s60, s37, 0
	s_add_u32 s61, s24, 0x100
	v_mov_b32_e32 v2, 0
	s_addc_u32 s64, s25, 0
	s_mov_b32 s65, -2
	v_mov_b32_e32 v3, v2
	v_mov_b64_e32 v[4:5], 0
	v_mov_b64_e32 v[6:7], 0
	v_mov_b64_e32 v[8:9], 0
	v_mov_b64_e32 v[10:11], 0
	v_mov_b64_e32 v[12:13], 0
	v_mov_b64_e32 v[14:15], 0
	v_mov_b64_e32 v[16:17], 0
	v_mov_b64_e32 v[18:19], 0
	v_mov_b64_e32 v[20:21], 0
	v_mov_b64_e32 v[22:23], 0
	v_mov_b64_e32 v[24:25], 0
	v_mov_b64_e32 v[26:27], 0
	v_mov_b64_e32 v[28:29], 0
	v_mov_b64_e32 v[30:31], 0
	v_mov_b64_e32 v[32:33], 0
	v_mov_b64_e32 v[34:35], 0
	v_mov_b64_e32 v[36:37], 0
	v_mov_b64_e32 v[38:39], 0
	v_mov_b64_e32 v[40:41], 0
	v_mov_b64_e32 v[42:43], 0
	v_mov_b64_e32 v[44:45], 0
	v_mov_b64_e32 v[46:47], 0
	v_mov_b64_e32 v[48:49], 0
	v_mov_b64_e32 v[50:51], 0
	v_mov_b64_e32 v[52:53], 0
	v_mov_b64_e32 v[54:55], 0
	v_mov_b64_e32 v[56:57], 0
	v_mov_b64_e32 v[58:59], 0
	v_mov_b64_e32 v[60:61], 0
	v_mov_b64_e32 v[62:63], 0
	v_mov_b64_e32 v[64:65], 0
	v_mov_b64_e32 v[66:67], 0
	v_mov_b64_e32 v[68:69], 0
	v_mov_b64_e32 v[70:71], 0
	v_mov_b64_e32 v[72:73], 0
	v_mov_b64_e32 v[74:75], 0
	v_mov_b64_e32 v[76:77], 0
	v_mov_b64_e32 v[78:79], 0
	v_mov_b64_e32 v[80:81], 0
	v_mov_b64_e32 v[82:83], 0
	v_mov_b64_e32 v[84:85], 0
	v_mov_b64_e32 v[86:87], 0
	v_mov_b64_e32 v[88:89], 0
	v_mov_b64_e32 v[90:91], 0
	v_mov_b64_e32 v[92:93], 0
	v_mov_b64_e32 v[94:95], 0
	v_mov_b64_e32 v[96:97], 0
	v_mov_b64_e32 v[98:99], 0
	v_mov_b64_e32 v[100:101], 0
	v_mov_b64_e32 v[102:103], 0
	v_mov_b64_e32 v[104:105], 0
	v_mov_b64_e32 v[106:107], 0
	v_mov_b64_e32 v[108:109], 0
	v_mov_b64_e32 v[110:111], 0
	v_mov_b64_e32 v[112:113], 0
	v_mov_b64_e32 v[114:115], 0
	v_mov_b64_e32 v[116:117], 0
	v_mov_b64_e32 v[118:119], 0
	v_mov_b64_e32 v[120:121], 0
	v_mov_b64_e32 v[122:123], 0
	v_mov_b64_e32 v[124:125], 0
	v_mov_b64_e32 v[126:127], 0
	v_mov_b64_e32 v[128:129], 0
	v_add_u32_e32 v250, 0x10000, v155
	v_add_u32_e32 v251, 0x14000, v155
	v_add_u32_e32 v252, 0x18000, v155
	v_add_u32_e32 v253, 0x1c000, v155
; #define PG8_STAGE(bufoff, gbase, voff) do { _Pragma("unroll") for (int _i = 0; _i < 2; ++_i) \
;         __builtin_amdgcn_global_load_lds((const unsigned*)((const char*)(gbase) + (voff)[_i]), (LAS unsigned*)(lds + (bufoff) + ldsw + _i * 8192), 16, 0, 0); } while (0)
; #define PG8_LDA(dst, b, h) do { _Pragma("unroll") for (int m = 0; m < 4; ++m) _Pragma("unroll") for (int k = 0; k < 2; ++k) dst[m][k] = *(const LAS bf16x8*)(lds + PG8_SA(b, h) + aoff + m * 2048 + k * 1024); } while (0)
; #define PG8_LDB(dst, b, h) do { _Pragma("unroll") for (int n = 0; n < 2; ++n) _Pragma("unroll") for (int k = 0; k < 2; ++k) dst[n][k] = *(const LAS bf16x8*)(lds + PG8_SB(b, h) + boff + n * 2048 + k * 1024); } while (0)
; #define PG8_WAIT_V(n) asm volatile("s_waitcnt vmcnt(" #n ")" ::: "memory")
; #define PG8_BAR __builtin_amdgcn_s_barrier()
; template <class Epi>
; __device__ __forceinline__ void gemm_phase(const int tid, LAS unsigned char* lds, const Gemm g, const StaticOrder& S, const Epi& E) {
;     ...
;         for (int t = 0; t < nt; t += 2) {
;             const bool last = (t == nt - 2);
;             const char* a2 = last ? nA : cA + (size_t)(t + 2) * kstep; const char* b2 = last ? nB : cB + (size_t)(t + 2) * kstep;
;             const char* a3 = a2 + kstep; const char* b3 = b2 + kstep;
;             PG8_LDB(B0, 0, 0); PG8_SCHED; PG8_LDA(At, 0, 0);
;             PG8_WAIT_L(8); PG8_BAR; PG8_WAIT_L(0); PG8_MMA(0, 0, At, B0); PG8_BAR; PG8_SCHED;
;             PG8_LDB(B1, 0, 1); PG8_STAGE(PG8_SB(0, 0), b2, voffB);
;             PG8_BAR; PG8_WAIT_L(0); PG8_MMA(0, 1, At, B1); PG8_BAR;
;             PG8_LDA(At, 0, 1); PG8_STAGE(PG8_SA(0, 0), a2, voffA);
;             PG8_BAR; PG8_WAIT_L(0); PG8_MMA(1, 0, At, B0); PG8_BAR; PG8_SCHED;
;             PG8_STAGE(PG8_SB(0, 1), b2 + hstep, voffB);
;             { const int first_ = __builtin_amdgcn_readfirstlane((ui > 0 && t == 0) ? 1 : 0);
;               if constexpr (Epi::SMIN == 8) asm volatile("s_cmp_eq_u32 %0, 0\n\ts_cbranch_scc1 .Lws_a%=\n\ts_waitcnt vmcnt(14)\n\ts_branch .Lws_b%=\n.Lws_a%=:\n\ts_waitcnt vmcnt(6)\n.Lws_b%=:" :: "s"(first_) : "memory", "scc");
;               else if constexpr (Epi::SMIN == 24) asm volatile("s_cmp_eq_u32 %0, 0\n\ts_cbranch_scc1 .Lws_a%=\n\ts_waitcnt vmcnt(30)\n\ts_branch .Lws_b%=\n.Lws_a%=:\n\ts_waitcnt vmcnt(6)\n.Lws_b%=:" :: "s"(first_) : "memory", "scc");
;               else PG8_WAIT_V(6); }
.LBB0_448:
	s_add_i32 s66, 0, 0x10000
	ds_read_b128 v[130:133], v250
	ds_read_b128 v[142:145], v250 offset:1024
	ds_read_b128 v[146:149], v250 offset:2048
	ds_read_b128 v[150:153], v250 offset:3072
	s_cmp_eq_u32 s65, 28
	s_cselect_b32 s25, s13, s60
	s_cselect_b32 s24, s57, s59
	s_cselect_b32 s37, s11, s64
	s_cselect_b32 s36, s58, s61
	ds_read_b128 v[160:163], v158
	ds_read_b128 v[164:167], v158 offset:1024
	ds_read_b128 v[168:171], v158 offset:2048
	ds_read_b128 v[172:175], v158 offset:3072
	ds_read_b128 v[176:179], v158 offset:4096
	ds_read_b128 v[180:183], v158 offset:5120
	ds_read_b128 v[184:187], v158 offset:6144
	ds_read_b128 v[188:191], v158 offset:7168
	s_waitcnt lgkmcnt(8)
	s_barrier
	s_setprio 1
	s_waitcnt lgkmcnt(7)
	v_mfma_f32_16x16x32_bf16 v[126:129], v[130:133], v[160:163], v[126:129]
	v_mfma_f32_16x16x32_bf16 v[118:121], v[146:149], v[160:163], v[118:121]
	s_waitcnt lgkmcnt(5)
	v_mfma_f32_16x16x32_bf16 v[110:113], v[130:133], v[168:171], v[110:113]
	v_mfma_f32_16x16x32_bf16 v[102:105], v[146:149], v[168:171], v[102:105]
	s_waitcnt lgkmcnt(3)
	v_mfma_f32_16x16x32_bf16 v[94:97], v[130:133], v[176:179], v[94:97]
	v_mfma_f32_16x16x32_bf16 v[86:89], v[146:149], v[176:179], v[86:89]
	s_waitcnt lgkmcnt(1)
	v_mfma_f32_16x16x32_bf16 v[78:81], v[130:133], v[184:187], v[78:81]
	v_mfma_f32_16x16x32_bf16 v[70:73], v[146:149], v[184:187], v[70:73]
	v_mfma_f32_16x16x32_bf16 v[126:129], v[142:145], v[164:167], v[126:129]
	v_mfma_f32_16x16x32_bf16 v[118:121], v[150:153], v[164:167], v[118:121]
	v_mfma_f32_16x16x32_bf16 v[110:113], v[142:145], v[172:175], v[110:113]
	v_mfma_f32_16x16x32_bf16 v[102:105], v[150:153], v[172:175], v[102:105]
	v_mfma_f32_16x16x32_bf16 v[94:97], v[142:145], v[180:183], v[94:97]
	v_mfma_f32_16x16x32_bf16 v[86:89], v[150:153], v[180:183], v[86:89]
	s_waitcnt lgkmcnt(0)
	v_mfma_f32_16x16x32_bf16 v[78:81], v[142:145], v[188:191], v[78:81]
	v_mfma_f32_16x16x32_bf16 v[70:73], v[150:153], v[188:191], v[70:73]
	s_setprio 0
	s_barrier
	s_add_i32 s68, 0, 0x14000
	s_add_i32 s66, s66, s28
	s_mov_b32 m0, s66
	ds_read_b128 v[192:195], v251
	ds_read_b128 v[196:199], v251 offset:1024
	ds_read_b128 v[200:203], v251 offset:2048
	ds_read_b128 v[204:207], v251 offset:3072
	global_load_lds_dwordx4 v0, s[36:37]
	s_add_i32 m0, s66, 0x2000
	s_nop 0
	global_load_lds_dwordx4 v134, s[36:37]
	s_barrier
	s_setprio 1
	s_waitcnt lgkmcnt(3)
	v_mfma_f32_16x16x32_bf16 v[122:125], v[192:195], v[160:163], v[122:125]
	s_waitcnt lgkmcnt(1)
	v_mfma_f32_16x16x32_bf16 v[114:117], v[200:203], v[160:163], v[114:117]
	v_mfma_f32_16x16x32_bf16 v[106:109], v[192:195], v[168:171], v[106:109]
	v_mfma_f32_16x16x32_bf16 v[98:101], v[200:203], v[168:171], v[98:101]
	v_mfma_f32_16x16x32_bf16 v[90:93], v[192:195], v[176:179], v[90:93]
	v_mfma_f32_16x16x32_bf16 v[82:85], v[200:203], v[176:179], v[82:85]
	v_mfma_f32_16x16x32_bf16 v[74:77], v[192:195], v[184:187], v[74:77]
	v_mfma_f32_16x16x32_bf16 v[66:69], v[200:203], v[184:187], v[66:69]
	v_mfma_f32_16x16x32_bf16 v[122:125], v[196:199], v[164:167], v[122:125]
	s_waitcnt lgkmcnt(0)
	v_mfma_f32_16x16x32_bf16 v[114:117], v[204:207], v[164:167], v[114:117]
	v_mfma_f32_16x16x32_bf16 v[106:109], v[196:199], v[172:175], v[106:109]
	v_mfma_f32_16x16x32_bf16 v[98:101], v[204:207], v[172:175], v[98:101]
	v_mfma_f32_16x16x32_bf16 v[90:93], v[196:199], v[180:183], v[90:93]
	v_mfma_f32_16x16x32_bf16 v[82:85], v[204:207], v[180:183], v[82:85]
	v_mfma_f32_16x16x32_bf16 v[74:77], v[196:199], v[188:191], v[74:77]
	v_mfma_f32_16x16x32_bf16 v[66:69], v[204:207], v[188:191], v[66:69]
	s_setprio 0
	s_mov_b32 m0, s30
	s_barrier
	ds_read_b128 v[160:163], v158 offset:16384
	ds_read_b128 v[164:167], v158 offset:17408
	ds_read_b128 v[168:171], v158 offset:18432
	ds_read_b128 v[172:175], v158 offset:19456
	ds_read_b128 v[176:179], v158 offset:20480
	ds_read_b128 v[180:183], v158 offset:21504
	ds_read_b128 v[184:187], v158 offset:22528
	ds_read_b128 v[188:191], v158 offset:23552
	global_load_lds_dwordx4 v138, s[24:25]
	s_mov_b32 m0, s38
	s_nop 0
	global_load_lds_dwordx4 v136, s[24:25]
	s_barrier
	s_setprio 1
	s_waitcnt lgkmcnt(7)
	v_mfma_f32_16x16x32_bf16 v[62:65], v[130:133], v[160:163], v[62:65]
	v_mfma_f32_16x16x32_bf16 v[54:57], v[146:149], v[160:163], v[54:57]
	s_waitcnt lgkmcnt(5)
	v_mfma_f32_16x16x32_bf16 v[46:49], v[130:133], v[168:171], v[46:49]
	v_mfma_f32_16x16x32_bf16 v[38:41], v[146:149], v[168:171], v[38:41]
	s_waitcnt lgkmcnt(3)
	v_mfma_f32_16x16x32_bf16 v[30:33], v[130:133], v[176:179], v[30:33]
	v_mfma_f32_16x16x32_bf16 v[22:25], v[146:149], v[176:179], v[22:25]
	s_waitcnt lgkmcnt(1)
	v_mfma_f32_16x16x32_bf16 v[14:17], v[130:133], v[184:187], v[14:17]
	v_mfma_f32_16x16x32_bf16 v[6:9], v[146:149], v[184:187], v[6:9]
	v_mfma_f32_16x16x32_bf16 v[62:65], v[142:145], v[164:167], v[62:65]
	v_mfma_f32_16x16x32_bf16 v[54:57], v[150:153], v[164:167], v[54:57]
	v_mfma_f32_16x16x32_bf16 v[46:49], v[142:145], v[172:175], v[46:49]
	v_mfma_f32_16x16x32_bf16 v[38:41], v[150:153], v[172:175], v[38:41]
	v_mfma_f32_16x16x32_bf16 v[30:33], v[142:145], v[180:183], v[30:33]
	v_mfma_f32_16x16x32_bf16 v[22:25], v[150:153], v[180:183], v[22:25]
	s_waitcnt lgkmcnt(0)
	v_mfma_f32_16x16x32_bf16 v[14:17], v[142:145], v[188:191], v[14:17]
	v_mfma_f32_16x16x32_bf16 v[6:9], v[150:153], v[188:191], v[6:9]
	s_setprio 0
	s_barrier
	s_add_u32 s66, s36, 0x80000
	s_addc_u32 s67, s37, 0
	s_add_i32 s68, s68, s28
	s_mov_b32 m0, s68
	s_nop 0
	global_load_lds_dwordx4 v0, s[66:67]
	s_add_i32 m0, s68, 0x2000
	s_cmp_eq_u32 s65, -2
	global_load_lds_dwordx4 v134, s[66:67]
	s_cselect_b64 s[66:67], -1, 0
	s_and_b64 s[66:67], s[22:23], s[66:67]
	v_cndmask_b32_e64 v130, 0, 1, s[66:67]
	s_nop 0
	v_readfirstlane_b32 s66, v130
	s_and_b32 s66, s66, 1
	s_cmp_eq_u32 s66, 0
	s_cbranch_scc1 .Lws_a1
	s_waitcnt vmcnt(14)
	s_branch .Lws_b1

; #define PG8_STAGE(bufoff, gbase, voff) do { _Pragma("unroll") for (int _i = 0; _i < 2; ++_i) \
;         __builtin_amdgcn_global_load_lds((const unsigned*)((const char*)(gbase) + (voff)[_i]), (LAS unsigned*)(lds + (bufoff) + ldsw + _i * 8192), 16, 0, 0); } while (0)
; #define PG8_LDA(dst, b, h) do { _Pragma("unroll") for (int m = 0; m < 4; ++m) _Pragma("unroll") for (int k = 0; k < 2; ++k) dst[m][k] = *(const LAS bf16x8*)(lds + PG8_SA(b, h) + aoff + m * 2048 + k * 1024); } while (0)
; #define PG8_LDB(dst, b, h) do { _Pragma("unroll") for (int n = 0; n < 2; ++n) _Pragma("unroll") for (int k = 0; k < 2; ++k) dst[n][k] = *(const LAS bf16x8*)(lds + PG8_SB(b, h) + boff + n * 2048 + k * 1024); } while (0)
; #define PG8_MMA(ai, bj, At, Bt) do { __builtin_amdgcn_s_setprio(1); _Pragma("unroll") for (int m = 0; m < 4; ++m) _Pragma("unroll") for (int n = 0; n < 2; ++n) _Pragma("unroll") for (int k = 0; k < 2; ++k) \
;         acc[ai][bj][m][n] = __builtin_amdgcn_mfma_f32_16x16x32_bf16(Bt[n][k], At[m][k], acc[ai][bj][m][n], 0, 0, 0); __builtin_amdgcn_s_setprio(0); } while (0)
; #define PG8_WAIT_L(n) asm volatile("s_waitcnt lgkmcnt(" #n ")" ::: "memory")
; #define PG8_BAR __builtin_amdgcn_s_barrier()
; #define PG8_SCHED __builtin_amdgcn_sched_barrier(0)
; template <class Epi>
; __device__ __forceinline__ void gemm_phase(const int tid, LAS unsigned char* lds, const Gemm g, const StaticOrder& S, const Epi& E) {
;     ...
;             PG8_BAR; PG8_MMA(1, 1, At, B1); PG8_BAR;
;             PG8_LDB(B0, 1, 0); PG8_SCHED; PG8_LDA(At, 1, 0); PG8_STAGE(PG8_SA(0, 1), a2 + hstep, voffA);
;             PG8_WAIT_L(8); PG8_BAR; PG8_WAIT_L(0); PG8_MMA(0, 0, At, B0); PG8_BAR; PG8_SCHED;
;             PG8_LDB(B1, 1, 1); PG8_STAGE(PG8_SB(1, 0), b3, voffB);
;             PG8_BAR; PG8_WAIT_L(0); PG8_MMA(0, 1, At, B1); PG8_BAR;
;             PG8_LDA(At, 1, 1); PG8_STAGE(PG8_SA(1, 0), a3, voffA);
;             PG8_BAR; PG8_WAIT_L(0); PG8_MMA(1, 0, At, B0); PG8_BAR; PG8_SCHED;
.Lws_b1:
	s_barrier
	s_setprio 1
	v_mfma_f32_16x16x32_bf16 v[58:61], v[192:195], v[160:163], v[58:61]
	v_mfma_f32_16x16x32_bf16 v[50:53], v[200:203], v[160:163], v[50:53]
	v_mfma_f32_16x16x32_bf16 v[42:45], v[192:195], v[168:171], v[42:45]
	v_mfma_f32_16x16x32_bf16 v[34:37], v[200:203], v[168:171], v[34:37]
	v_mfma_f32_16x16x32_bf16 v[26:29], v[192:195], v[176:179], v[26:29]
	v_mfma_f32_16x16x32_bf16 v[18:21], v[200:203], v[176:179], v[18:21]
	v_mfma_f32_16x16x32_bf16 v[10:13], v[192:195], v[184:187], v[10:13]
	v_mfma_f32_16x16x32_bf16 v[2:5], v[200:203], v[184:187], v[2:5]
	v_mfma_f32_16x16x32_bf16 v[58:61], v[196:199], v[164:167], v[58:61]
	v_mfma_f32_16x16x32_bf16 v[50:53], v[204:207], v[164:167], v[50:53]
	v_mfma_f32_16x16x32_bf16 v[42:45], v[196:199], v[172:175], v[42:45]
	v_mfma_f32_16x16x32_bf16 v[34:37], v[204:207], v[172:175], v[34:37]
	v_mfma_f32_16x16x32_bf16 v[26:29], v[196:199], v[180:183], v[26:29]
	v_mfma_f32_16x16x32_bf16 v[18:21], v[204:207], v[180:183], v[18:21]
	v_mfma_f32_16x16x32_bf16 v[10:13], v[196:199], v[188:191], v[10:13]
	v_mfma_f32_16x16x32_bf16 v[2:5], v[204:207], v[188:191], v[2:5]
	s_setprio 0
	s_add_i32 s68, 0, 0x18000
	s_barrier
	ds_read_b128 v[130:133], v252
	ds_read_b128 v[142:145], v252 offset:1024
	ds_read_b128 v[146:149], v252 offset:2048
	ds_read_b128 v[150:153], v252 offset:3072
	s_add_u32 s66, s24, 0x80000
	s_addc_u32 s67, s25, 0
	s_mov_b32 m0, s39
	ds_read_b128 v[160:163], v158 offset:32768
	ds_read_b128 v[164:167], v158 offset:33792
	ds_read_b128 v[168:171], v158 offset:34816
	ds_read_b128 v[172:175], v158 offset:35840
	ds_read_b128 v[176:179], v158 offset:36864
	ds_read_b128 v[180:183], v158 offset:37888
	ds_read_b128 v[184:187], v158 offset:38912
	ds_read_b128 v[188:191], v158 offset:39936
	global_load_lds_dwordx4 v138, s[66:67]
	s_mov_b32 m0, s46
	s_nop 0
	global_load_lds_dwordx4 v136, s[66:67]
	s_waitcnt lgkmcnt(8)
	s_barrier
	s_setprio 1
	s_waitcnt lgkmcnt(7)
	v_mfma_f32_16x16x32_bf16 v[126:129], v[130:133], v[160:163], v[126:129]
	v_mfma_f32_16x16x32_bf16 v[118:121], v[146:149], v[160:163], v[118:121]
	s_waitcnt lgkmcnt(5)
	v_mfma_f32_16x16x32_bf16 v[110:113], v[130:133], v[168:171], v[110:113]
	v_mfma_f32_16x16x32_bf16 v[102:105], v[146:149], v[168:171], v[102:105]
	s_waitcnt lgkmcnt(3)
	v_mfma_f32_16x16x32_bf16 v[94:97], v[130:133], v[176:179], v[94:97]
	v_mfma_f32_16x16x32_bf16 v[86:89], v[146:149], v[176:179], v[86:89]
	s_waitcnt lgkmcnt(1)
	v_mfma_f32_16x16x32_bf16 v[78:81], v[130:133], v[184:187], v[78:81]
	v_mfma_f32_16x16x32_bf16 v[70:73], v[146:149], v[184:187], v[70:73]
	v_mfma_f32_16x16x32_bf16 v[126:129], v[142:145], v[164:167], v[126:129]
	v_mfma_f32_16x16x32_bf16 v[118:121], v[150:153], v[164:167], v[118:121]
	v_mfma_f32_16x16x32_bf16 v[110:113], v[142:145], v[172:175], v[110:113]
	v_mfma_f32_16x16x32_bf16 v[102:105], v[150:153], v[172:175], v[102:105]
	v_mfma_f32_16x16x32_bf16 v[94:97], v[142:145], v[180:183], v[94:97]
	v_mfma_f32_16x16x32_bf16 v[86:89], v[150:153], v[180:183], v[86:89]
	s_waitcnt lgkmcnt(0)
	v_mfma_f32_16x16x32_bf16 v[78:81], v[142:145], v[188:191], v[78:81]
	v_mfma_f32_16x16x32_bf16 v[70:73], v[150:153], v[188:191], v[70:73]
	s_setprio 0
	s_barrier
	s_add_i32 s66, 0, 0x1c000
	s_add_i32 s67, s68, s28
	s_add_i32 m0, s67, 0xffffff80
	ds_read_b128 v[192:195], v253
	ds_read_b128 v[196:199], v253 offset:1024
	ds_read_b128 v[200:203], v253 offset:2048
	ds_read_b128 v[204:207], v253 offset:3072
	global_load_lds_dwordx4 v0, s[36:37] offset:128
	s_add_i32 m0, s67, 0x1f80
	s_nop 0
	global_load_lds_dwordx4 v134, s[36:37] offset:128
	s_barrier
	s_setprio 1
	s_waitcnt lgkmcnt(3)
	v_mfma_f32_16x16x32_bf16 v[122:125], v[192:195], v[160:163], v[122:125]
	s_waitcnt lgkmcnt(1)
	v_mfma_f32_16x16x32_bf16 v[114:117], v[200:203], v[160:163], v[114:117]
	v_mfma_f32_16x16x32_bf16 v[106:109], v[192:195], v[168:171], v[106:109]
	v_mfma_f32_16x16x32_bf16 v[98:101], v[200:203], v[168:171], v[98:101]
	v_mfma_f32_16x16x32_bf16 v[90:93], v[192:195], v[176:179], v[90:93]
	v_mfma_f32_16x16x32_bf16 v[82:85], v[200:203], v[176:179], v[82:85]
	v_mfma_f32_16x16x32_bf16 v[74:77], v[192:195], v[184:187], v[74:77]
	v_mfma_f32_16x16x32_bf16 v[66:69], v[200:203], v[184:187], v[66:69]
	v_mfma_f32_16x16x32_bf16 v[122:125], v[196:199], v[164:167], v[122:125]
	s_waitcnt lgkmcnt(0)
	v_mfma_f32_16x16x32_bf16 v[114:117], v[204:207], v[164:167], v[114:117]
	v_mfma_f32_16x16x32_bf16 v[106:109], v[196:199], v[172:175], v[106:109]
	v_mfma_f32_16x16x32_bf16 v[98:101], v[204:207], v[172:175], v[98:101]
	v_mfma_f32_16x16x32_bf16 v[90:93], v[196:199], v[180:183], v[90:93]
	v_mfma_f32_16x16x32_bf16 v[82:85], v[204:207], v[180:183], v[82:85]
	v_mfma_f32_16x16x32_bf16 v[74:77], v[196:199], v[188:191], v[74:77]
	v_mfma_f32_16x16x32_bf16 v[66:69], v[204:207], v[188:191], v[66:69]
	s_setprio 0
	s_add_i32 m0, s47, 0xffffff80
	s_barrier
	ds_read_b128 v[160:163], v158 offset:49152
	ds_read_b128 v[164:167], v158 offset:50176
	ds_read_b128 v[168:171], v158 offset:51200
	ds_read_b128 v[172:175], v158 offset:52224
	ds_read_b128 v[176:179], v158 offset:53248
	ds_read_b128 v[180:183], v158 offset:54272
	ds_read_b128 v[184:187], v158 offset:55296
	ds_read_b128 v[188:191], v158 offset:56320
	global_load_lds_dwordx4 v138, s[24:25] offset:128
	s_add_i32 m0, s48, 0xffffff80
	s_nop 0
	global_load_lds_dwordx4 v136, s[24:25] offset:128
	s_barrier
; #define PG8_STAGE(bufoff, gbase, voff) do { _Pragma("unroll") for (int _i = 0; _i < 2; ++_i) \
;         __builtin_amdgcn_global_load_lds((const unsigned*)((const char*)(gbase) + (voff)[_i]), (LAS unsigned*)(lds + (bufoff) + ldsw + _i * 8192), 16, 0, 0); } while (0)
; #define PG8_MMA(ai, bj, At, Bt) do { __builtin_amdgcn_s_setprio(1); _Pragma("unroll") for (int m = 0; m < 4; ++m) _Pragma("unroll") for (int n = 0; n < 2; ++n) _Pragma("unroll") for (int k = 0; k < 2; ++k) \
;         acc[ai][bj][m][n] = __builtin_amdgcn_mfma_f32_16x16x32_bf16(Bt[n][k], At[m][k], acc[ai][bj][m][n], 0, 0, 0); __builtin_amdgcn_s_setprio(0); } while (0)
; #define PG8_WAIT_V(n) asm volatile("s_waitcnt vmcnt(" #n ")" ::: "memory")
; #define PG8_WAIT_L(n) asm volatile("s_waitcnt lgkmcnt(" #n ")" ::: "memory")
; #define PG8_BAR __builtin_amdgcn_s_barrier()
; #define PG8_SCHED __builtin_amdgcn_sched_barrier(0)
; template <class Epi>
; __device__ __forceinline__ void gemm_phase(const int tid, LAS unsigned char* lds, const Gemm g, const StaticOrder& S, const Epi& E) {
;     ...
;             PG8_BAR; PG8_WAIT_L(0); PG8_MMA(1, 0, At, B0); PG8_BAR; PG8_SCHED;
;             PG8_STAGE(PG8_SB(1, 1), b3 + hstep, voffB);
;             PG8_WAIT_V(6); PG8_BAR; PG8_STAGE(PG8_SA(1, 1), a3 + hstep, voffA);
;             PG8_MMA(1, 1, At, B1); PG8_BAR;
;         }
;     __device__ __forceinline__ void operator()(const AccT& acc, const pg8::Unit& u, int wr, int wc, int fr, int fq, pg8::RsCache& rsc) const {
;         const int row0 = u.pm * 256 + wr * 64 + fr, col0 = u.pn * 128 + wc * 32 + 8 * fq;
;         if (rsc.pm != u.pm) {
	s_setprio 1
	s_waitcnt lgkmcnt(7)
	v_mfma_f32_16x16x32_bf16 v[62:65], v[130:133], v[160:163], v[62:65]
	v_mfma_f32_16x16x32_bf16 v[54:57], v[146:149], v[160:163], v[54:57]
	s_waitcnt lgkmcnt(5)
	v_mfma_f32_16x16x32_bf16 v[46:49], v[130:133], v[168:171], v[46:49]
	v_mfma_f32_16x16x32_bf16 v[38:41], v[146:149], v[168:171], v[38:41]
	s_waitcnt lgkmcnt(3)
	v_mfma_f32_16x16x32_bf16 v[30:33], v[130:133], v[176:179], v[30:33]
	v_mfma_f32_16x16x32_bf16 v[22:25], v[146:149], v[176:179], v[22:25]
	s_waitcnt lgkmcnt(1)
	v_mfma_f32_16x16x32_bf16 v[14:17], v[130:133], v[184:187], v[14:17]
	v_mfma_f32_16x16x32_bf16 v[6:9], v[146:149], v[184:187], v[6:9]
	v_mfma_f32_16x16x32_bf16 v[62:65], v[142:145], v[164:167], v[62:65]
	v_mfma_f32_16x16x32_bf16 v[54:57], v[150:153], v[164:167], v[54:57]
	v_mfma_f32_16x16x32_bf16 v[46:49], v[142:145], v[172:175], v[46:49]
	v_mfma_f32_16x16x32_bf16 v[38:41], v[150:153], v[172:175], v[38:41]
	v_mfma_f32_16x16x32_bf16 v[30:33], v[142:145], v[180:183], v[30:33]
	v_mfma_f32_16x16x32_bf16 v[22:25], v[150:153], v[180:183], v[22:25]
	s_waitcnt lgkmcnt(0)
	v_mfma_f32_16x16x32_bf16 v[14:17], v[142:145], v[188:191], v[14:17]
	v_mfma_f32_16x16x32_bf16 v[6:9], v[150:153], v[188:191], v[6:9]
	s_setprio 0
	s_barrier
	s_add_u32 s36, s36, 0x80080
	s_addc_u32 s37, s37, 0
	s_add_i32 s66, s66, s28
	s_mov_b32 m0, s66
	s_nop 0
	global_load_lds_dwordx4 v0, s[36:37]
	s_add_i32 m0, s66, 0x2000
	s_add_u32 s24, s24, 0x80080
	s_addc_u32 s25, s25, 0
	global_load_lds_dwordx4 v134, s[36:37]
	s_mov_b32 m0, s49
	s_waitcnt vmcnt(6)
	s_barrier
	global_load_lds_dwordx4 v138, s[24:25]
	s_mov_b32 m0, s50
	s_nop 0
	global_load_lds_dwordx4 v136, s[24:25]
	s_setprio 1
	v_mfma_f32_16x16x32_bf16 v[58:61], v[192:195], v[160:163], v[58:61]
	v_mfma_f32_16x16x32_bf16 v[50:53], v[200:203], v[160:163], v[50:53]
	v_mfma_f32_16x16x32_bf16 v[42:45], v[192:195], v[168:171], v[42:45]
	v_mfma_f32_16x16x32_bf16 v[34:37], v[200:203], v[168:171], v[34:37]
	v_mfma_f32_16x16x32_bf16 v[26:29], v[192:195], v[176:179], v[26:29]
	v_mfma_f32_16x16x32_bf16 v[18:21], v[200:203], v[176:179], v[18:21]
	v_mfma_f32_16x16x32_bf16 v[10:13], v[192:195], v[184:187], v[10:13]
	v_mfma_f32_16x16x32_bf16 v[2:5], v[200:203], v[184:187], v[2:5]
	v_mfma_f32_16x16x32_bf16 v[58:61], v[196:199], v[164:167], v[58:61]
	v_mfma_f32_16x16x32_bf16 v[50:53], v[204:207], v[164:167], v[50:53]
	v_mfma_f32_16x16x32_bf16 v[42:45], v[196:199], v[172:175], v[42:45]
	v_mfma_f32_16x16x32_bf16 v[34:37], v[204:207], v[172:175], v[34:37]
	v_mfma_f32_16x16x32_bf16 v[26:29], v[196:199], v[180:183], v[26:29]
	v_mfma_f32_16x16x32_bf16 v[18:21], v[204:207], v[180:183], v[18:21]
	v_mfma_f32_16x16x32_bf16 v[10:13], v[196:199], v[188:191], v[10:13]
	v_mfma_f32_16x16x32_bf16 v[2:5], v[204:207], v[188:191], v[2:5]
	s_setprio 0
	s_add_i32 s65, s65, 2
	s_add_u32 s59, s59, 0x100
	s_addc_u32 s60, s60, 0
	s_add_u32 s61, s61, 0x100
	s_addc_u32 s64, s64, 0
	s_cmp_gt_u32 s65, 29
	s_barrier
	s_cbranch_scc0 .LBB0_448
	v_lshl_add_u32 v150, s51, 8, v154
	s_cmp_lg_u32 s56, s51
	v_ashrrev_i32_e32 v151, 31, v150
	s_mov_b64 s[22:23], -1
	v_or_b32_e32 v148, 16, v150
	v_or_b32_e32 v146, 32, v150
	v_or_b32_e32 v144, 48, v150
	v_add_u32_e32 v152, 0x80, v150
	s_cbranch_scc0 .LBB0_453
; __device__ __forceinline__ void rows_rstd4(const float* ssqp, int rbase, int fq, float (&rs)[4]) {
;     f32x4 pa_[4], pb_[4];
; #pragma unroll
;     for (int m = 0; m < 4; ++m) { const float* q = ssqp + (size_t)(rbase + m * 16) * 32 + 8 * fq; pa_[m] = *(const f32x4*)q; pb_[m] = *(const f32x4*)(q + 4); }
;     asm volatile("" ::: "memory");
; #pragma unroll
;     for (int m = 0; m < 4; ++m) { const f32x4 a = pa_[m], b = pb_[m];
;         float t = ((a[0] + a[1]) + (a[2] + a[3])) + ((b[0] + b[1]) + (b[2] + b[3]));
;         t = xadd<16>(t); t = xadd<32>(t);
;         rs[m] = __builtin_amdgcn_rsqf(t * (1.0f / DM) + EPS); }
; }
;     __device__ __forceinline__ void operator()(const AccT& acc, const pg8::Unit& u, int wr, int wc, int fr, int fq, pg8::RsCache& rsc) const {
;     ...
;         if (rsc.pm != u.pm) {
;             float r0[4], r1[4]; rows_rstd4(ssq, row0, fq, r0); rows_rstd4(ssq, row0 + 128, fq, r1);
;             if (fq == 0) {
; #pragma unroll
;                 for (int m = 0; m < 4; ++m) { rsc.rl[m * 16 + fr] = r0[m]; rsc.rl[64 + m * 16 + fr] = r1[m]; } }
;             rsc.pm = u.pm; asm volatile("s_waitcnt lgkmcnt(0)" ::: "memory"); }
	v_lshlrev_b64 v[130:131], 7, v[150:151]
	v_lshl_add_u64 v[130:131], v[140:141], 0, v[130:131]
	global_load_dwordx4 v[160:163], v[130:131], off offset:16
	global_load_dwordx4 v[164:167], v[130:131], off
	v_ashrrev_i32_e32 v149, 31, v148
	v_lshlrev_b64 v[132:133], 7, v[148:149]
	v_lshl_add_u64 v[132:133], v[140:141], 0, v[132:133]
	global_load_dwordx4 v[168:171], v[132:133], off offset:16
	global_load_dwordx4 v[172:175], v[132:133], off
	v_ashrrev_i32_e32 v147, 31, v146
	v_lshlrev_b64 v[132:133], 7, v[146:147]
	v_lshl_add_u64 v[132:133], v[140:141], 0, v[132:133]
	global_load_dwordx4 v[176:179], v[132:133], off offset:16
	global_load_dwordx4 v[180:183], v[132:133], off
	v_ashrrev_i32_e32 v145, 31, v144
	v_lshlrev_b64 v[132:133], 7, v[144:145]
	v_lshl_add_u64 v[132:133], v[140:141], 0, v[132:133]
	global_load_dwordx4 v[184:187], v[132:133], off offset:16
	global_load_dwordx4 v[188:191], v[132:133], off
	s_movk_i32 s11, 0x4000
	s_mov_b64 s[22:23], 0x4800
	s_waitcnt vmcnt(0)
	v_add_f32_e32 v142, v162, v163
	v_add_f32_e32 v132, v164, v165
	v_add_f32_e32 v133, v166, v167
	v_add_f32_e32 v132, v132, v133
	v_add_f32_e32 v133, v160, v161
	v_add_f32_e32 v133, v133, v142
	v_add_f32_e32 v132, v132, v133
	ds_swizzle_b32 v133, v132 offset:swizzle(SWAP,16)
	v_add_f32_e32 v142, v170, v171
	s_waitcnt lgkmcnt(0)
	v_add_f32_e32 v151, v132, v133
	v_add_f32_e32 v132, v172, v173
	v_add_f32_e32 v133, v174, v175
	v_add_f32_e32 v132, v132, v133
	v_add_f32_e32 v133, v168, v169
	v_add_f32_e32 v133, v133, v142
	v_add_f32_e32 v132, v132, v133
	ds_swizzle_b32 v133, v132 offset:swizzle(SWAP,16)
	v_add_f32_e32 v142, v178, v179
	v_add_co_u32_e32 v174, vcc, s11, v130
	s_movk_i32 s11, 0x5000
	s_waitcnt lgkmcnt(0)
	v_add_f32_e32 v159, v132, v133
	v_add_f32_e32 v132, v180, v181
	v_add_f32_e32 v133, v182, v183
	v_add_f32_e32 v132, v132, v133
	v_add_f32_e32 v133, v176, v177
	v_add_f32_e32 v133, v133, v142
	v_add_f32_e32 v132, v132, v133
	ds_swizzle_b32 v133, v132 offset:swizzle(SWAP,16)
	v_add_f32_e32 v142, v186, v187
	v_addc_co_u32_e32 v175, vcc, 0, v131, vcc
	v_mov_b32_e32 v153, v151
	s_waitcnt lgkmcnt(0)
	v_add_f32_e32 v161, v132, v133
	v_add_f32_e32 v132, v188, v189
	v_add_f32_e32 v133, v190, v191
	v_add_f32_e32 v132, v132, v133
	v_add_f32_e32 v133, v184, v185
	v_add_f32_e32 v133, v133, v142
	v_add_f32_e32 v132, v132, v133
	ds_swizzle_b32 v133, v132 offset:swizzle(SWAP,16)
	v_add_u32_e32 v142, 0x80, v150
	v_ashrrev_i32_e32 v143, 31, v142
	v_add_co_u32_e32 v190, vcc, s11, v130
	s_waitcnt lgkmcnt(0)
	v_add_f32_e32 v163, v132, v133
	v_lshlrev_b64 v[132:133], 7, v[142:143]
	v_lshl_add_u64 v[132:133], v[140:141], 0, v[132:133]
	global_load_dwordx4 v[166:169], v[132:133], off offset:16
	global_load_dwordx4 v[170:173], v[132:133], off
	v_lshl_add_u64 v[132:133], v[130:131], 0, s[22:23]
	global_load_dwordx4 v[174:177], v[174:175], off offset:2048
	s_nop 0
	global_load_dwordx4 v[178:181], v[132:133], off offset:16
	s_mov_b64 s[22:23], 0x5000
	v_lshl_add_u64 v[132:133], v[130:131], 0, s[22:23]
	v_addc_co_u32_e32 v191, vcc, 0, v131, vcc
	s_mov_b64 s[22:23], 0x5800
	global_load_dwordx4 v[182:185], v[190:191], off
	global_load_dwordx4 v[186:189], v[132:133], off offset:16
	v_lshl_add_u64 v[130:131], v[130:131], 0, s[22:23]
	global_load_dwordx4 v[190:193], v[190:191], off offset:2048
	s_nop 0
	global_load_dwordx4 v[130:133], v[130:131], off offset:16
	v_mov_b32_e32 v160, v159
	v_mov_b32_e32 v162, v161
	v_mov_b32_e32 v164, v163
	v_permlane32_swap_b32_e32 v151, v153
	v_permlane32_swap_b32_e32 v159, v160
	v_permlane32_swap_b32_e32 v161, v162
	v_permlane32_swap_b32_e32 v163, v164
	s_waitcnt vmcnt(7)
	v_add_f32_e32 v166, v166, v167
	v_add_f32_e32 v167, v168, v169
	v_add_f32_e32 v166, v166, v167
	s_waitcnt vmcnt(5)
	v_add_f32_e32 v167, v174, v175
	v_add_f32_e32 v168, v176, v177
	v_add_f32_e32 v165, v170, v171
	v_add_f32_e32 v170, v172, v173
	v_add_f32_e32 v167, v167, v168
	s_waitcnt vmcnt(4)
	v_add_f32_e32 v168, v178, v179
	v_add_f32_e32 v169, v180, v181
	v_add_f32_e32 v165, v165, v170
	v_add_f32_e32 v168, v168, v169
	s_waitcnt vmcnt(3)
	v_add_f32_e32 v169, v182, v183
	v_add_f32_e32 v170, v184, v185
	v_add_f32_e32 v169, v169, v170
	s_waitcnt vmcnt(2)
	v_add_f32_e32 v170, v186, v187
	v_add_f32_e32 v171, v188, v189
	v_add_f32_e32 v170, v170, v171
	s_waitcnt vmcnt(1)
	v_add_f32_e32 v171, v190, v191
	v_add_f32_e32 v172, v192, v193
	s_waitcnt vmcnt(0)
	v_add_f32_e32 v130, v130, v131
	v_add_f32_e32 v131, v132, v133
	v_add_f32_e32 v171, v171, v172
	v_add_f32_e32 v130, v130, v131
	v_add_f32_e32 v165, v165, v166
	v_add_f32_e32 v167, v167, v168
	v_add_f32_e32 v169, v169, v170
	v_add_f32_e32 v130, v171, v130
	ds_swizzle_b32 v166, v165 offset:swizzle(SWAP,16)
	ds_swizzle_b32 v168, v167 offset:swizzle(SWAP,16)
	ds_swizzle_b32 v170, v169 offset:swizzle(SWAP,16)
	ds_swizzle_b32 v131, v130 offset:swizzle(SWAP,16)
	s_waitcnt lgkmcnt(3)
	v_add_f32_e32 v165, v165, v166
	s_waitcnt lgkmcnt(2)
	v_add_f32_e32 v167, v167, v168
	s_waitcnt lgkmcnt(1)
	v_add_f32_e32 v169, v169, v170
	s_waitcnt lgkmcnt(0)
	v_add_f32_e32 v130, v130, v131
	v_mov_b32_e32 v166, v165
	v_mov_b32_e32 v168, v167
	v_mov_b32_e32 v170, v169
	v_mov_b32_e32 v131, v130
	v_permlane32_swap_b32_e32 v165, v166
	v_permlane32_swap_b32_e32 v167, v168
	v_permlane32_swap_b32_e32 v169, v170
	v_permlane32_swap_b32_e32 v130, v131
	s_and_saveexec_b64 s[22:23], s[4:5]
	s_cbranch_execz .LBB0_452
	v_add_f32_e32 v159, v159, v160
	v_add_f32_e32 v151, v151, v153
	v_add_f32_e32 v132, v167, v168
	v_add_f32_e32 v133, v165, v166
	v_fmamk_f32 v159, v159, 0x3a000000, v242
	v_fmamk_f32 v151, v151, 0x3a000000, v242
	v_fmamk_f32 v132, v132, 0x3a000000, v242
	v_fmamk_f32 v133, v133, 0x3a000000, v242
	v_add_f32_e32 v163, v163, v164
	v_add_f32_e32 v161, v161, v162
	v_rsq_f32_e32 v159, v159
	v_rsq_f32_e32 v151, v151
	v_add_f32_e32 v130, v130, v131
	v_add_f32_e32 v131, v169, v170
	v_rsq_f32_e32 v132, v132
	v_rsq_f32_e32 v133, v133
	v_fmamk_f32 v163, v163, 0x3a000000, v242
	v_fmamk_f32 v153, v161, 0x3a000000, v242
	v_fmamk_f32 v130, v130, 0x3a000000, v242
	v_fmamk_f32 v131, v131, 0x3a000000, v242
	v_rsq_f32_e32 v163, v163
	v_rsq_f32_e32 v153, v153
	v_rsq_f32_e32 v130, v130
	v_rsq_f32_e32 v131, v131
	ds_write2_b32 v156, v151, v159 offset1:16
	ds_write2_b32 v156, v133, v132 offset0:64 offset1:80
	ds_write2_b32 v156, v153, v163 offset0:32 offset1:48
	ds_write2_b32 v156, v131, v130 offset0:96 offset1:112
